# GEMM weights stored K32-blocked [K/32][N][32] by the convert phase so every B-tile DMA fetches full 128-byte lines (was 16 half-lines per instruction)
# speedup vs baseline: 1.0933x; 1.0652x over previous
; DI unsigned pk2(float lo, float hi) { f32x2 v = {lo, hi}; bf16x2_t r = __builtin_convertvector(v, bf16x2_t); return __builtin_bit_cast(unsigned, r); }
; DI void cvt_job(const float* src, bf16_t* dst, int K, int Nn, int NnPad, int remap, char* smem) {
;     ...
;         {
;             const int nl = tid >> 2, part = tid & 3;
;             u32x4 v0, v1;
; #pragma unroll
;             for (int j = 0; j < 4; ++j) {
;                 v0[j] = pk2(tile[(part * 16 + 2 * j) * 65 + nl], tile[(part * 16 + 2 * j + 1) * 65 + nl]);
;                 v1[j] = pk2(tile[(part * 16 + 8 + 2 * j) * 65 + nl], tile[(part * 16 + 8 + 2 * j + 1) * 65 + nl]);
;             }
;             bf16_t* d = dst + (size_t)(nt * 64 + nl) * K + kt * 64 + part * 16;
;             *(u32x4*)d = v0; *(u32x4*)(d + 8) = v1;
;         }
.LBB0_16:
	s_or_b64 exec, exec, s[22:23]
	s_waitcnt vmcnt(1)
	ds_write_b32 v12, v2 offset:14560
	s_waitcnt vmcnt(0)
	ds_write_b32 v12, v17 offset:15600
	s_waitcnt lgkmcnt(0)
	s_barrier
	ds_read2_b32 v[6:7], v10 offset1:130
	ds_read2_b32 v[18:19], v11 offset0:65 offset1:195
	ds_read2_b32 v[20:21], v13 offset0:8 offset1:73
	s_add_i32 s22, s33, s24
	s_ashr_i32 s23, s22, 31
	s_add_i32 s34, s34, s29
	s_waitcnt lgkmcnt(1)
	v_cvt_pk_bf16_f32 v18, v6, v18
	s_waitcnt lgkmcnt(0)
	v_cvt_pk_bf16_f32 v22, v20, v21
	ds_read2_b32 v[20:21], v13 offset0:138 offset1:203
	ds_read2_b32 v[24:25], v14 offset0:4 offset1:134
	ds_read2_b32 v[26:27], v15 offset0:69 offset1:199
	ds_read2_b32 v[28:29], v16 offset0:12 offset1:77
	v_cvt_pk_bf16_f32 v19, v7, v19
	ds_read2_b32 v[6:7], v16 offset0:142 offset1:207
	s_waitcnt lgkmcnt(4)
	v_cvt_pk_bf16_f32 v23, v20, v21
	s_waitcnt lgkmcnt(2)
	v_cvt_pk_bf16_f32 v21, v25, v27
	s_add_i32 s33, s33, s31
	v_cvt_pk_bf16_f32 v20, v24, v26
	s_waitcnt lgkmcnt(0)
	v_cvt_pk_bf16_f32 v25, v6, v7
	v_add_u32_e32 v6, s35, v9
	v_ashrrev_i32_e32 v7, 31, v6
	v_lshlrev_b64 v[6:7], 6, v[6:7]
	v_lshl_add_u64 v[6:7], s[20:21], 0, v[6:7]
	s_mul_i32 s98, s22, 0x1800
	s_mov_b32 s99, 0
	v_lshl_add_u64 v[6:7], s[98:99], 0, v[6:7]
	v_lshrrev_b32_e32 v254, 6, v4
	v_mul_u32_u24_e32 v254, 0x30000, v254
	v_and_or_b32 v254, v4, 32, v254
	v_mov_b32_e32 v255, 0
	v_lshl_add_u64 v[6:7], v[6:7], 0, v[254:255]
	s_cmpk_lt_i32 s34, 0x300
	v_cvt_pk_bf16_f32 v24, v28, v29
	global_store_dwordx4 v[6:7], v[18:21], off
	global_store_dwordx4 v[6:7], v[22:25], off offset:16
	s_barrier
	s_cbranch_scc0 .LBB0_41

; DI unsigned pk2(float lo, float hi) { f32x2 v = {lo, hi}; bf16x2_t r = __builtin_convertvector(v, bf16x2_t); return __builtin_bit_cast(unsigned, r); }
; DI void cvt_job(const float* src, bf16_t* dst, int K, int Nn, int NnPad, int remap, char* smem) {
;     ...
;         {
;             const int nl = tid >> 2, part = tid & 3;
;             u32x4 v0, v1;
; #pragma unroll
;             for (int j = 0; j < 4; ++j) {
;                 v0[j] = pk2(tile[(part * 16 + 2 * j) * 65 + nl], tile[(part * 16 + 2 * j + 1) * 65 + nl]);
;                 v1[j] = pk2(tile[(part * 16 + 8 + 2 * j) * 65 + nl], tile[(part * 16 + 8 + 2 * j + 1) * 65 + nl]);
;             }
;             bf16_t* d = dst + (size_t)(nt * 64 + nl) * K + kt * 64 + part * 16;
;             *(u32x4*)d = v0; *(u32x4*)(d + 8) = v1;
;         }
.LBB0_44:
	s_or_b64 exec, exec, s[22:23]
	s_waitcnt vmcnt(1)
	ds_write_b32 v12, v2 offset:14560
	s_waitcnt vmcnt(0)
	ds_write_b32 v12, v5 offset:15600
	v_add_u32_e32 v2, 0x800, v11
	s_waitcnt lgkmcnt(0)
	s_barrier
	ds_read2_b32 v[6:7], v10 offset1:130
	ds_read2_b32 v[14:15], v11 offset0:65 offset1:195
	ds_read2_b32 v[16:17], v2 offset0:8 offset1:73
	s_add_i32 s22, s29, s34
	s_ashr_i32 s23, s22, 31
	v_mov_b32_e32 v5, v3
	s_waitcnt lgkmcnt(1)
	v_cvt_pk_bf16_f32 v14, v6, v14
	s_waitcnt lgkmcnt(0)
	v_cvt_pk_bf16_f32 v18, v16, v17
	ds_read2_b32 v[16:17], v2 offset0:138 offset1:203
	v_add_u32_e32 v2, 0x400, v10
	ds_read2_b32 v[20:21], v2 offset0:4 offset1:134
	v_add_u32_e32 v2, 0x400, v11
	ds_read2_b32 v[22:23], v2 offset0:69 offset1:199
	v_add_u32_e32 v2, 0xc00, v11
	v_cvt_pk_bf16_f32 v15, v7, v15
	ds_read2_b32 v[6:7], v2 offset0:142 offset1:207
	s_waitcnt lgkmcnt(3)
	v_cvt_pk_bf16_f32 v19, v16, v17
	s_waitcnt lgkmcnt(1)
	v_cvt_pk_bf16_f32 v17, v21, v23
	ds_read2_b32 v[24:25], v2 offset0:12 offset1:77
	s_add_i32 s31, s31, s24
	s_waitcnt lgkmcnt(1)
	v_cvt_pk_bf16_f32 v21, v6, v7
	v_add_u32_e32 v6, s33, v9
	v_ashrrev_i32_e32 v7, 31, v6
	v_lshlrev_b64 v[6:7], 6, v[6:7]
	v_lshl_add_u64 v[6:7], s[20:21], 0, v[6:7]
	s_mul_i32 s98, s22, 0x800
	s_mov_b32 s99, 0
	v_lshl_add_u64 v[6:7], s[98:99], 0, v[6:7]
	s_add_i32 s29, s29, s25
	v_cvt_pk_bf16_f32 v16, v20, v22
	v_lshrrev_b32_e32 v254, 6, v4
	v_mul_u32_u24_e32 v254, 0x10000, v254
	v_and_or_b32 v254, v4, 32, v254
	v_mov_b32_e32 v255, 0
	v_lshl_add_u64 v[6:7], v[6:7], 0, v[254:255]
	s_cmpk_lt_i32 s31, 0x100
	s_waitcnt lgkmcnt(0)
	v_cvt_pk_bf16_f32 v20, v24, v25
	global_store_dwordx4 v[6:7], v[14:17], off
	global_store_dwordx4 v[6:7], v[18:21], off offset:16
	s_barrier
	s_cbranch_scc0 .LBB0_61

; DI unsigned pk2(float lo, float hi) { f32x2 v = {lo, hi}; bf16x2_t r = __builtin_convertvector(v, bf16x2_t); return __builtin_bit_cast(unsigned, r); }
; DI void cvt_job(const float* src, bf16_t* dst, int K, int Nn, int NnPad, int remap, char* smem) {
;     ...
;         {
;             const int nl = tid >> 2, part = tid & 3;
;             u32x4 v0, v1;
; #pragma unroll
;             for (int j = 0; j < 4; ++j) {
;                 v0[j] = pk2(tile[(part * 16 + 2 * j) * 65 + nl], tile[(part * 16 + 2 * j + 1) * 65 + nl]);
;                 v1[j] = pk2(tile[(part * 16 + 8 + 2 * j) * 65 + nl], tile[(part * 16 + 8 + 2 * j + 1) * 65 + nl]);
;             }
;             bf16_t* d = dst + (size_t)(nt * 64 + nl) * K + kt * 64 + part * 16;
;             *(u32x4*)d = v0; *(u32x4*)(d + 8) = v1;
;         }
.LBB0_63:
	s_or_b64 exec, exec, s[24:25]
	s_waitcnt vmcnt(1)
	ds_write_b32 v12, v2 offset:14560
	s_waitcnt vmcnt(0)
	ds_write_b32 v12, v5 offset:15600
	v_add_u32_e32 v2, 0x800, v11
	s_waitcnt lgkmcnt(0)
	s_barrier
	ds_read2_b32 v[6:7], v10 offset1:130
	ds_read2_b32 v[14:15], v11 offset0:65 offset1:195
	ds_read2_b32 v[16:17], v2 offset0:8 offset1:73
	s_add_i32 s24, s33, s36
	s_ashr_i32 s25, s24, 31
	v_mov_b32_e32 v5, v3
	s_waitcnt lgkmcnt(1)
	v_cvt_pk_bf16_f32 v14, v6, v14
	s_waitcnt lgkmcnt(0)
	v_cvt_pk_bf16_f32 v18, v16, v17
	ds_read2_b32 v[16:17], v2 offset0:138 offset1:203
	v_add_u32_e32 v2, 0x400, v10
	ds_read2_b32 v[20:21], v2 offset0:4 offset1:134
	v_add_u32_e32 v2, 0x400, v11
	ds_read2_b32 v[22:23], v2 offset0:69 offset1:199
	v_add_u32_e32 v2, 0xc00, v11
	v_cvt_pk_bf16_f32 v15, v7, v15
	ds_read2_b32 v[6:7], v2 offset0:142 offset1:207
	s_waitcnt lgkmcnt(3)
	v_cvt_pk_bf16_f32 v19, v16, v17
	s_waitcnt lgkmcnt(1)
	v_cvt_pk_bf16_f32 v17, v21, v23
	ds_read2_b32 v[24:25], v2 offset0:12 offset1:77
	s_add_i32 s34, s34, s29
	s_waitcnt lgkmcnt(1)
	v_cvt_pk_bf16_f32 v21, v6, v7
	v_add_u32_e32 v6, s35, v9
	v_ashrrev_i32_e32 v7, 31, v6
	v_lshlrev_b64 v[6:7], 6, v[6:7]
	v_lshl_add_u64 v[6:7], s[22:23], 0, v[6:7]
	s_mul_i32 s98, s24, 0x2000
	s_mov_b32 s99, 0
	v_lshl_add_u64 v[6:7], s[98:99], 0, v[6:7]
	s_add_i32 s33, s33, s31
	v_cvt_pk_bf16_f32 v16, v20, v22
	v_lshrrev_b32_e32 v254, 6, v4
	v_mul_u32_u24_e32 v254, 0x40000, v254
	v_and_or_b32 v254, v4, 32, v254
	v_mov_b32_e32 v255, 0
	v_lshl_add_u64 v[6:7], v[6:7], 0, v[254:255]
	s_cmpk_lt_i32 s34, 0x400
	s_waitcnt lgkmcnt(0)
	v_cvt_pk_bf16_f32 v20, v24, v25
	global_store_dwordx4 v[6:7], v[14:17], off
	global_store_dwordx4 v[6:7], v[18:21], off offset:16
	s_barrier
	s_cbranch_scc0 .LBB0_80

; DI unsigned pk2(float lo, float hi) { f32x2 v = {lo, hi}; bf16x2_t r = __builtin_convertvector(v, bf16x2_t); return __builtin_bit_cast(unsigned, r); }
; DI void cvt_job(const float* src, bf16_t* dst, int K, int Nn, int NnPad, int remap, char* smem) {
;     ...
;         {
;             const int nl = tid >> 2, part = tid & 3;
;             u32x4 v0, v1;
; #pragma unroll
;             for (int j = 0; j < 4; ++j) {
;                 v0[j] = pk2(tile[(part * 16 + 2 * j) * 65 + nl], tile[(part * 16 + 2 * j + 1) * 65 + nl]);
;                 v1[j] = pk2(tile[(part * 16 + 8 + 2 * j) * 65 + nl], tile[(part * 16 + 8 + 2 * j + 1) * 65 + nl]);
;             }
;             bf16_t* d = dst + (size_t)(nt * 64 + nl) * K + kt * 64 + part * 16;
;             *(u32x4*)d = v0; *(u32x4*)(d + 8) = v1;
;         }
.LBB0_82:
	s_or_b64 exec, exec, s[22:23]
	s_waitcnt vmcnt(1)
	ds_write_b32 v12, v2 offset:14560
	s_waitcnt vmcnt(0)
	ds_write_b32 v12, v5 offset:15600
	v_add_u32_e32 v2, 0x800, v11
	s_waitcnt lgkmcnt(0)
	s_barrier
	ds_read2_b32 v[6:7], v10 offset1:130
	ds_read2_b32 v[14:15], v11 offset0:65 offset1:195
	ds_read2_b32 v[16:17], v2 offset0:8 offset1:73
	s_add_i32 s22, s29, s34
	s_ashr_i32 s23, s22, 31
	v_mov_b32_e32 v5, v3
	s_waitcnt lgkmcnt(1)
	v_cvt_pk_bf16_f32 v14, v6, v14
	s_waitcnt lgkmcnt(0)
	v_cvt_pk_bf16_f32 v18, v16, v17
	ds_read2_b32 v[16:17], v2 offset0:138 offset1:203
	v_add_u32_e32 v2, 0x400, v10
	ds_read2_b32 v[20:21], v2 offset0:4 offset1:134
	v_add_u32_e32 v2, 0x400, v11
	ds_read2_b32 v[22:23], v2 offset0:69 offset1:199
	v_add_u32_e32 v2, 0xc00, v11
	v_cvt_pk_bf16_f32 v15, v7, v15
	ds_read2_b32 v[6:7], v2 offset0:142 offset1:207
	s_waitcnt lgkmcnt(3)
	v_cvt_pk_bf16_f32 v19, v16, v17
	s_waitcnt lgkmcnt(1)
	v_cvt_pk_bf16_f32 v17, v21, v23
	ds_read2_b32 v[24:25], v2 offset0:12 offset1:77
	s_add_i32 s31, s31, s24
	s_waitcnt lgkmcnt(1)
	v_cvt_pk_bf16_f32 v21, v6, v7
	v_add_u32_e32 v6, s33, v9
	v_ashrrev_i32_e32 v7, 31, v6
	v_lshlrev_b64 v[6:7], 6, v[6:7]
	v_lshl_add_u64 v[6:7], s[18:19], 0, v[6:7]
	s_mul_i32 s98, s22, 0x800
	s_mov_b32 s99, 0
	v_lshl_add_u64 v[6:7], s[98:99], 0, v[6:7]
	s_add_i32 s29, s29, s25
	v_cvt_pk_bf16_f32 v16, v20, v22
	v_lshrrev_b32_e32 v254, 6, v4
	v_mul_u32_u24_e32 v254, 0x10000, v254
	v_and_or_b32 v254, v4, 32, v254
	v_mov_b32_e32 v255, 0
	v_lshl_add_u64 v[6:7], v[6:7], 0, v[254:255]
	s_cmpk_lt_i32 s31, 0x400
	s_waitcnt lgkmcnt(0)
	v_cvt_pk_bf16_f32 v20, v24, v25
	global_store_dwordx4 v[6:7], v[14:17], off
	global_store_dwordx4 v[6:7], v[18:21], off offset:16
	s_barrier
	s_cbranch_scc0 .LBB0_99

; DI f32x4 mfma(bf16x8 a, bf16x8 b, f32x4 c) { return __builtin_amdgcn_mfma_f32_16x16x32_bf16(a, b, c, 0, 0, 0); }
; #define G_LOAD(PA, PB, STEP) do { _Pragma("unroll") for (int i_ = 0; i_ < 2; ++i_) ra[i_] = *(const u32x4*)((PA) + (size_t)(64 * i_) * K + (STEP) * 32); \
;         _Pragma("unroll") for (int i_ = 0; i_ < 4; ++i_) rb[i_] = *(const u32x4*)((PB) + (size_t)(64 * i_) * K + (STEP) * 32); } while (0)
; #define G_STORE(BUF) do { _Pragma("unroll") for (int i_ = 0; i_ < 2; ++i_) *(u32x4*)(sA + (BUF) * 128 * 40 + (lrow + 64 * i_) * 40 + lcc * 8) = ra[i_]; \
;         _Pragma("unroll") for (int i_ = 0; i_ < 4; ++i_) *(u32x4*)(sB + (BUF) * 256 * 40 + (lrow + 64 * i_) * 40 + lcc * 8) = rb[i_]; } while (0)
; template <int EPI> ...
;     ...
;     const int idx0 = blockIdx.x >> 3;
;     if (idx0 < perX) {
;         int mt0, nt0; tile_of(idx0, mt0, nt0);
;         const bf16_t* A0 = A + (size_t)(mt0 * 128 + lrow) * K + lcc * 8;
;         const bf16_t* B0 = Bt + (size_t)(nt0 * 256 + lrowp) * K + lcc * 8;
;         G_LOAD(A0, B0, 0);
;         G_STORE(0);
;         G_LOAD(A0, B0, 1);
;         __syncthreads();
;     }
;     ...
;         for (int kt = 0; kt < nk; ++kt) {
;             const int buf = kt & 1;
;             const bf16_t* a_ = sA + buf * 128 * 40 + (wr * 64 + fr) * 40 + fq * 8;
;             const bf16_t* b_ = sB + buf * 256 * 40 + (wc * 128 + fr) * 40 + fq * 8;
;             bf16x8 af[4];
; #pragma unroll
;             for (int i = 0; i < 4; ++i) af[i] = *(const bf16x8*)(a_ + i * 16 * 40);
; #pragma unroll
;             for (int jh = 0; jh < 2; ++jh) {
;                 bf16x8 bfr[4];
; #pragma unroll
;                 for (int j = 0; j < 4; ++j) bfr[j] = *(const bf16x8*)(b_ + (jh * 4 + j) * 16 * 40);
; #pragma unroll
;                 for (int i = 0; i < 4; ++i)
; #pragma unroll
;                     for (int j = 0; j < 4; ++j) acc[i][jh * 4 + j] = mfma(bfr[j], af[i], acc[i][jh * 4 + j]);
;             }
;             G_STORE(buf ^ 1);
;             {
;                 const bool cur = kt + 2 < nk;
;                 const bf16_t* pa = cur ? Ag : An; const bf16_t* pb = cur ? Bg : Bn;
;                 const int st = cur ? kt + 2 : kt + 2 - nk;
;                 G_LOAD(pa, pb, st);
;             }
.LBB0_162:
	v_readlane_b32 s9, v253, 4
	v_readlane_b32 s12, v253, 6
	v_readlane_b32 s13, v253, 5
	s_nop 3
	s_cmp_eq_u32 s13, 0
	s_cbranch_scc1 .Lg162_entry
	v_and_b32_e32 v8, 63, v210
	v_lshrrev_b32_e32 v9, 6, v210
	s_nop 0
	v_readfirstlane_b32 s13, v9
	v_lshrrev_b32_e32 v9, 4, v8
	v_sub_u32_e32 v10, 0, v9
	v_and_b32_e32 v10, 3, v10
	v_and_b32_e32 v11, 3, v8
	v_xor_b32_e32 v11, v11, v10
	v_lshrrev_b32_e32 v12, 2, v8
	v_lshlrev_b32_e32 v0, 11, v12
	v_lshl_add_u32 v0, v11, 4, v0
	s_lshl_b32 vcc_lo, s13, 16
	v_add_u32_e32 v0, vcc_lo, v0
	v_add_u32_e32 v0, 0x1000, v0
	v_add_u32_e32 v1, 0x7c00, v0
	v_and_b32_e32 v13, 3, v12
	v_lshl_add_u32 v13, v9, 3, v13
	v_lshlrev_b32_e32 v2, 6, v13
	v_lshl_add_u32 v2, v11, 4, v2
	s_lshl_b32 vcc_lo, s13, 12
	v_add_u32_e32 v2, vcc_lo, v2
	v_add_u32_e32 v2, 0x800, v2
	v_add_u32_e32 v3, 0xfffffd00, v2
	v_add_u32_e32 v4, 0x1000, v2
	v_add_u32_e32 v5, 0xd00, v2
	v_and_b32_e32 v10, 15, v8
	v_lshrrev_b32_e32 v11, 2, v10
	v_sub_u32_e32 v11, 0, v11
	v_and_b32_e32 v11, 3, v11
	v_xor_b32_e32 v11, v9, v11
	v_lshlrev_b32_e32 v6, 6, v10
	v_lshl_add_u32 v6, v11, 4, v6
	s_lshr_b32 vcc_lo, s13, 1
	s_mul_i32 vcc_lo, vcc_lo, 0x3000
	s_and_b32 vcc_hi, s13, 1
	s_mul_i32 vcc_hi, vcc_hi, 0x3000
	s_add_u32 vcc_hi, vcc_hi, 0x800
	v_add_u32_e32 v7, vcc_hi, v6
	v_add_u32_e32 v6, vcc_lo, v6
	s_mul_i32 s12, s13, 0x1800
	v_writelane_b32 v253, s12, 6
	v_writelane_b32 v253, 0, 5
	v_readlane_b32 vcc_lo, v253, 0
	v_readlane_b32 vcc_hi, v253, 1
	s_lshl_b32 s13, s6, 18
	s_nop 1
	s_add_u32 s98, vcc_lo, s13
	s_addc_u32 s99, vcc_hi, 0
	s_sub_u32 s98, s98, 0x1000
	s_subb_u32 s99, s99, 0
	v_readlane_b32 vcc_lo, v253, 2
	v_readlane_b32 vcc_hi, v253, 3
	s_lshl_b32 s13, s5, 14
	s_nop 1
	s_add_u32 s100, vcc_lo, s13
	s_addc_u32 s101, vcc_hi, 0
	s_sub_u32 s100, s100, 0x1000
	s_subb_u32 s101, s101, 0
	s_add_u32 m0, s9, s12
	s_nop 0
	global_load_lds_dwordx4 v0, s[98:99]
	global_load_lds_dwordx4 v1, s[98:99] offset:1024
	global_load_lds_dwordx4 v2, s[100:101] offset:2048
	global_load_lds_dwordx4 v3, s[100:101] offset:3072
	s_add_u32 m0, m0, 0x1000
	s_nop 0
	global_load_lds_dwordx4 v4, s[100:101]
	global_load_lds_dwordx4 v5, s[100:101] offset:1024
	s_add_u32 s98, s98, 64
	s_addc_u32 s99, s99, 0
	s_add_u32 s100, s100, 0x30000
	s_addc_u32 s101, s101, 0
	s_add_u32 s13, s9, 0x6000
	s_cmp_eq_u32 s13, 0x12000
	s_cselect_b32 s13, 0, s13
	s_add_u32 m0, s13, s12
	s_nop 0
	global_load_lds_dwordx4 v0, s[98:99]
	global_load_lds_dwordx4 v1, s[98:99] offset:1024
	global_load_lds_dwordx4 v2, s[100:101] offset:2048
	global_load_lds_dwordx4 v3, s[100:101] offset:3072
	s_add_u32 m0, m0, 0x1000
	s_nop 0
	global_load_lds_dwordx4 v4, s[100:101]
	global_load_lds_dwordx4 v5, s[100:101] offset:1024
	s_add_u32 s98, s98, 64
	s_addc_u32 s99, s99, 0
	s_add_u32 s100, s100, 0x30000
	s_addc_u32 s101, s101, 0
	s_add_u32 s13, s13, 0x6000
	s_cmp_eq_u32 s13, 0x12000
	s_cselect_b32 s13, 0, s13
	s_add_u32 m0, s13, s12
	s_nop 0
	global_load_lds_dwordx4 v0, s[98:99]
	global_load_lds_dwordx4 v1, s[98:99] offset:1024
	global_load_lds_dwordx4 v2, s[100:101] offset:2048
	global_load_lds_dwordx4 v3, s[100:101] offset:3072
	s_add_u32 m0, m0, 0x1000
	s_nop 0
	global_load_lds_dwordx4 v4, s[100:101]
	global_load_lds_dwordx4 v5, s[100:101] offset:1024
	s_add_u32 s98, s98, 64
	s_addc_u32 s99, s99, 0
	s_add_u32 s100, s100, 0x30000
	s_addc_u32 s101, s101, 0

; DI f32x4 mfma(bf16x8 a, bf16x8 b, f32x4 c) { return __builtin_amdgcn_mfma_f32_16x16x32_bf16(a, b, c, 0, 0, 0); }
; #define G_LOAD(PA, PB, STEP) do { _Pragma("unroll") for (int i_ = 0; i_ < 2; ++i_) ra[i_] = *(const u32x4*)((PA) + (size_t)(64 * i_) * K + (STEP) * 32); \
;         _Pragma("unroll") for (int i_ = 0; i_ < 4; ++i_) rb[i_] = *(const u32x4*)((PB) + (size_t)(64 * i_) * K + (STEP) * 32); } while (0)
; #define G_STORE(BUF) do { _Pragma("unroll") for (int i_ = 0; i_ < 2; ++i_) *(u32x4*)(sA + (BUF) * 128 * 40 + (lrow + 64 * i_) * 40 + lcc * 8) = ra[i_]; \
;         _Pragma("unroll") for (int i_ = 0; i_ < 4; ++i_) *(u32x4*)(sB + (BUF) * 256 * 40 + (lrow + 64 * i_) * 40 + lcc * 8) = rb[i_]; } while (0)
; template <int EPI> ...
;     ...
;         for (int kt = 0; kt < nk; ++kt) {
;             const int buf = kt & 1;
;             const bf16_t* a_ = sA + buf * 128 * 40 + (wr * 64 + fr) * 40 + fq * 8;
;             const bf16_t* b_ = sB + buf * 256 * 40 + (wc * 128 + fr) * 40 + fq * 8;
;             bf16x8 af[4];
; #pragma unroll
;             for (int i = 0; i < 4; ++i) af[i] = *(const bf16x8*)(a_ + i * 16 * 40);
; #pragma unroll
;             for (int jh = 0; jh < 2; ++jh) {
;                 bf16x8 bfr[4];
; #pragma unroll
;                 for (int j = 0; j < 4; ++j) bfr[j] = *(const bf16x8*)(b_ + (jh * 4 + j) * 16 * 40);
; #pragma unroll
;                 for (int i = 0; i < 4; ++i)
; #pragma unroll
;                     for (int j = 0; j < 4; ++j) acc[i][jh * 4 + j] = mfma(bfr[j], af[i], acc[i][jh * 4 + j]);
;             }
;             G_STORE(buf ^ 1);
;             {
;                 const bool cur = kt + 2 < nk;
;                 const bf16_t* pa = cur ? Ag : An; const bf16_t* pb = cur ? Bg : Bn;
;                 const int st = cur ? kt + 2 : kt + 2 - nk;
;                 G_LOAD(pa, pb, st);
;             }
;             __syncthreads();
;         }
;     ...
; #pragma unroll
;         for (int i = 0; i < 4; ++i) {
;             const int m = mt * 128 + wr * 64 + i * 16 + fr;
;             float rsc = 1.f;
;             if (EPI != 2 && rs_in) rsc = rsqrtf(rs_in[m] * (1.f / DM) + 1e-6f);
.Lg162_swret:
	s_add_u32 m0, s9, s12
	v_mfma_f32_16x16x32_bf16 v[132:135], v[192:195], v[10:13], v[132:135]
	global_load_lds_dwordx4 v0, s[98:99]
	v_mfma_f32_16x16x32_bf16 v[128:131], v[196:199], v[10:13], v[128:131]
	v_mfma_f32_16x16x32_bf16 v[124:127], v[200:203], v[10:13], v[124:127]
	global_load_lds_dwordx4 v1, s[98:99] offset:1024
	v_mfma_f32_16x16x32_bf16 v[120:123], v[204:207], v[10:13], v[120:123]
	ds_read_b128 v[10:13], v8
	v_mfma_f32_16x16x32_bf16 v[100:103], v[192:195], v[14:17], v[100:103]
	global_load_lds_dwordx4 v2, s[100:101] offset:2048
	v_mfma_f32_16x16x32_bf16 v[96:99], v[196:199], v[14:17], v[96:99]
	v_mfma_f32_16x16x32_bf16 v[92:95], v[200:203], v[14:17], v[92:95]
	global_load_lds_dwordx4 v3, s[100:101] offset:3072
	v_mfma_f32_16x16x32_bf16 v[88:91], v[204:207], v[14:17], v[88:91]
	ds_read_b128 v[14:17], v8 offset:1024
	v_mfma_f32_16x16x32_bf16 v[68:71], v[192:195], v[18:21], v[68:71]
	s_add_u32 m0, m0, 0x1000
	v_mfma_f32_16x16x32_bf16 v[64:67], v[196:199], v[18:21], v[64:67]
	global_load_lds_dwordx4 v4, s[100:101]
	v_mfma_f32_16x16x32_bf16 v[60:63], v[200:203], v[18:21], v[60:63]
	v_mfma_f32_16x16x32_bf16 v[56:59], v[204:207], v[18:21], v[56:59]
	ds_read_b128 v[18:21], v8 offset:6144
	v_mfma_f32_16x16x32_bf16 v[36:39], v[192:195], v[152:155], v[36:39]
	global_load_lds_dwordx4 v5, s[100:101] offset:1024
	v_mfma_f32_16x16x32_bf16 v[32:35], v[196:199], v[152:155], v[32:35]
	v_mfma_f32_16x16x32_bf16 v[28:31], v[200:203], v[152:155], v[28:31]
	v_mfma_f32_16x16x32_bf16 v[24:27], v[204:207], v[152:155], v[24:27]
	ds_read_b128 v[152:155], v8 offset:7168
	ds_read_b128 v[192:195], v9 offset:6144
	ds_read_b128 v[196:199], v9 offset:7168
	ds_read_b128 v[200:203], v9 offset:8192
	ds_read_b128 v[204:207], v9 offset:9216
	s_add_u32 s98, s98, 64
	s_addc_u32 s99, s99, 0
	s_add_u32 s100, s100, 0x30000
	s_addc_u32 s101, s101, 0
	s_add_u32 s9, s9, 0x6000
	s_cmp_eq_u32 s9, 0x12000
	s_cselect_b32 s9, 0, s9
	s_add_u32 s4, s4, 1
	s_cmp_lt_u32 s4, 31
	s_cbranch_scc1 .Lg162_top
	s_waitcnt lgkmcnt(4)
	v_mfma_f32_16x16x32_bf16 v[148:151], v[160:163], v[10:13], v[148:151]
	v_mfma_f32_16x16x32_bf16 v[116:119], v[160:163], v[14:17], v[116:119]
	v_mfma_f32_16x16x32_bf16 v[84:87], v[160:163], v[18:21], v[84:87]
	v_mfma_f32_16x16x32_bf16 v[52:55], v[160:163], v[152:155], v[52:55]
	v_mfma_f32_16x16x32_bf16 v[144:147], v[174:177], v[10:13], v[144:147]
	v_mfma_f32_16x16x32_bf16 v[112:115], v[174:177], v[14:17], v[112:115]
	v_mfma_f32_16x16x32_bf16 v[80:83], v[174:177], v[18:21], v[80:83]
	v_mfma_f32_16x16x32_bf16 v[48:51], v[174:177], v[152:155], v[48:51]
	v_mfma_f32_16x16x32_bf16 v[140:143], v[178:181], v[10:13], v[140:143]
	v_mfma_f32_16x16x32_bf16 v[108:111], v[178:181], v[14:17], v[108:111]
	v_mfma_f32_16x16x32_bf16 v[76:79], v[178:181], v[18:21], v[76:79]
	v_mfma_f32_16x16x32_bf16 v[44:47], v[178:181], v[152:155], v[44:47]
	v_mfma_f32_16x16x32_bf16 v[136:139], v[182:185], v[10:13], v[136:139]
	v_mfma_f32_16x16x32_bf16 v[104:107], v[182:185], v[14:17], v[104:107]
	v_mfma_f32_16x16x32_bf16 v[72:75], v[182:185], v[18:21], v[72:75]
	v_mfma_f32_16x16x32_bf16 v[40:43], v[182:185], v[152:155], v[40:43]
	s_waitcnt vmcnt(6)
	s_waitcnt lgkmcnt(0)
	s_barrier
	s_add_u32 m0, s9, s12
	v_mfma_f32_16x16x32_bf16 v[132:135], v[192:195], v[10:13], v[132:135]
	global_load_lds_dwordx4 v0, s[98:99]
	v_mfma_f32_16x16x32_bf16 v[128:131], v[196:199], v[10:13], v[128:131]
	v_mfma_f32_16x16x32_bf16 v[124:127], v[200:203], v[10:13], v[124:127]
	global_load_lds_dwordx4 v1, s[98:99] offset:1024
	v_mfma_f32_16x16x32_bf16 v[120:123], v[204:207], v[10:13], v[120:123]
	v_mfma_f32_16x16x32_bf16 v[100:103], v[192:195], v[14:17], v[100:103]
	global_load_lds_dwordx4 v2, s[100:101] offset:2048
	v_mfma_f32_16x16x32_bf16 v[96:99], v[196:199], v[14:17], v[96:99]
	v_mfma_f32_16x16x32_bf16 v[92:95], v[200:203], v[14:17], v[92:95]
	global_load_lds_dwordx4 v3, s[100:101] offset:3072
	v_mfma_f32_16x16x32_bf16 v[88:91], v[204:207], v[14:17], v[88:91]
	v_mfma_f32_16x16x32_bf16 v[68:71], v[192:195], v[18:21], v[68:71]
	s_add_u32 m0, m0, 0x1000
	v_mfma_f32_16x16x32_bf16 v[64:67], v[196:199], v[18:21], v[64:67]
	global_load_lds_dwordx4 v4, s[100:101]
	v_mfma_f32_16x16x32_bf16 v[60:63], v[200:203], v[18:21], v[60:63]
	v_mfma_f32_16x16x32_bf16 v[56:59], v[204:207], v[18:21], v[56:59]
	v_mfma_f32_16x16x32_bf16 v[36:39], v[192:195], v[152:155], v[36:39]
	global_load_lds_dwordx4 v5, s[100:101] offset:1024
	v_mfma_f32_16x16x32_bf16 v[32:35], v[196:199], v[152:155], v[32:35]
	v_mfma_f32_16x16x32_bf16 v[28:31], v[200:203], v[152:155], v[28:31]
	v_mfma_f32_16x16x32_bf16 v[24:27], v[204:207], v[152:155], v[24:27]
	s_add_u32 s98, s98, 64
	s_addc_u32 s99, s99, 0
	s_add_u32 s100, s100, 0x30000
	s_addc_u32 s101, s101, 0
	s_add_u32 s9, s9, 0x6000
	s_cmp_eq_u32 s9, 0x12000
	s_cselect_b32 s9, 0, s9
	s_add_u32 s4, s4, 1
	s_branch .Lg162_end
.Lg162_sw:
	v_readlane_b32 vcc_lo, v253, 0
	v_readlane_b32 vcc_hi, v253, 1
	s_lshl_b32 s13, s7, 18
	s_nop 1
	s_add_u32 s98, vcc_lo, s13
	s_addc_u32 s99, vcc_hi, 0
	s_sub_u32 s98, s98, 0x1000
	s_subb_u32 s99, s99, 0
	v_readlane_b32 vcc_lo, v253, 2
	v_readlane_b32 vcc_hi, v253, 3
	s_lshl_b32 s13, s8, 14
	s_nop 1
	s_add_u32 s100, vcc_lo, s13
	s_addc_u32 s101, vcc_hi, 0
	s_sub_u32 s100, s100, 0x1000
	s_subb_u32 s101, s101, 0
	s_branch .Lg162_swret
.Lg162_end:
	s_setprio 0
	v_writelane_b32 v253, s9, 4
	v_lshl_add_u32 v154, s6, 7, v168
	v_ashrrev_i32_e32 v155, 31, v154
	v_mov_b32_e32 v160, 1.0
	s_and_b64 vcc, exec, s[80:81]
	s_cbranch_vccz .LBB0_165
	v_lshl_add_u64 v[152:153], v[154:155], 2, s[70:71]
	global_load_dword v152, v[152:153], off
	s_waitcnt vmcnt(0)
	v_fmamk_f32 v152, v152, 0x3a800000, v212
	v_mul_f32_e32 v153, 0x4b800000, v152
	v_cmp_gt_f32_e32 vcc, s78, v152
	s_nop 1
	v_cndmask_b32_e32 v152, v152, v153, vcc
	v_rsq_f32_e32 v152, v152
	s_nop 0
	v_mul_f32_e32 v153, 0x45800000, v152
	v_cndmask_b32_e32 v160, v152, v153, vcc

; DI f32x4 mfma(bf16x8 a, bf16x8 b, f32x4 c) { return __builtin_amdgcn_mfma_f32_16x16x32_bf16(a, b, c, 0, 0, 0); }
; #define G_LOAD(PA, PB, STEP) do { _Pragma("unroll") for (int i_ = 0; i_ < 2; ++i_) ra[i_] = *(const u32x4*)((PA) + (size_t)(64 * i_) * K + (STEP) * 32); \
;         _Pragma("unroll") for (int i_ = 0; i_ < 4; ++i_) rb[i_] = *(const u32x4*)((PB) + (size_t)(64 * i_) * K + (STEP) * 32); } while (0)
; #define G_STORE(BUF) do { _Pragma("unroll") for (int i_ = 0; i_ < 2; ++i_) *(u32x4*)(sA + (BUF) * 128 * 40 + (lrow + 64 * i_) * 40 + lcc * 8) = ra[i_]; \
;         _Pragma("unroll") for (int i_ = 0; i_ < 4; ++i_) *(u32x4*)(sB + (BUF) * 256 * 40 + (lrow + 64 * i_) * 40 + lcc * 8) = rb[i_]; } while (0)
; template <int EPI> ...
;     ...
;     const int idx0 = blockIdx.x >> 3;
;     if (idx0 < perX) {
;         int mt0, nt0; tile_of(idx0, mt0, nt0);
;         const bf16_t* A0 = A + (size_t)(mt0 * 128 + lrow) * K + lcc * 8;
;         const bf16_t* B0 = Bt + (size_t)(nt0 * 256 + lrowp) * K + lcc * 8;
;         G_LOAD(A0, B0, 0);
;         G_STORE(0);
;         G_LOAD(A0, B0, 1);
;         __syncthreads();
;     }
;     ...
;         for (int kt = 0; kt < nk; ++kt) {
;             const int buf = kt & 1;
;             const bf16_t* a_ = sA + buf * 128 * 40 + (wr * 64 + fr) * 40 + fq * 8;
;             const bf16_t* b_ = sB + buf * 256 * 40 + (wc * 128 + fr) * 40 + fq * 8;
;             bf16x8 af[4];
; #pragma unroll
;             for (int i = 0; i < 4; ++i) af[i] = *(const bf16x8*)(a_ + i * 16 * 40);
; #pragma unroll
;             for (int jh = 0; jh < 2; ++jh) {
;                 bf16x8 bfr[4];
; #pragma unroll
;                 for (int j = 0; j < 4; ++j) bfr[j] = *(const bf16x8*)(b_ + (jh * 4 + j) * 16 * 40);
; #pragma unroll
;                 for (int i = 0; i < 4; ++i)
; #pragma unroll
;                     for (int j = 0; j < 4; ++j) acc[i][jh * 4 + j] = mfma(bfr[j], af[i], acc[i][jh * 4 + j]);
;             }
;             G_STORE(buf ^ 1);
;             {
;                 const bool cur = kt + 2 < nk;
;                 const bf16_t* pa = cur ? Ag : An; const bf16_t* pb = cur ? Bg : Bn;
;                 const int st = cur ? kt + 2 : kt + 2 - nk;
;                 G_LOAD(pa, pb, st);
;             }
.LBB0_691:
	v_readlane_b32 s21, v253, 4
	v_readlane_b32 s22, v253, 6
	v_readlane_b32 s23, v253, 5
	s_nop 3
	s_cmp_eq_u32 s23, 0
	s_cbranch_scc1 .Lg691_entry
	v_and_b32_e32 v8, 63, v210
	v_lshrrev_b32_e32 v9, 6, v210
	s_nop 0
	v_readfirstlane_b32 s23, v9
	v_lshrrev_b32_e32 v9, 4, v8
	v_sub_u32_e32 v10, 0, v9
	v_and_b32_e32 v10, 3, v10
	v_and_b32_e32 v11, 3, v8
	v_xor_b32_e32 v11, v11, v10
	v_lshrrev_b32_e32 v12, 2, v8
	v_lshlrev_b32_e32 v0, 11, v12
	v_lshl_add_u32 v0, v11, 4, v0
	s_lshl_b32 vcc_lo, s23, 16
	v_add_u32_e32 v0, vcc_lo, v0
	v_add_u32_e32 v0, 0x1000, v0
	v_add_u32_e32 v1, 0x7c00, v0
	v_and_b32_e32 v13, 3, v12
	v_lshl_add_u32 v13, v9, 3, v13
	v_lshlrev_b32_e32 v2, 6, v13
	v_lshl_add_u32 v2, v11, 4, v2
	s_lshl_b32 vcc_lo, s23, 12
	v_add_u32_e32 v2, vcc_lo, v2
	v_add_u32_e32 v2, 0x800, v2
	v_add_u32_e32 v3, 0xfffffd00, v2
	v_add_u32_e32 v4, 0x1000, v2
	v_add_u32_e32 v5, 0xd00, v2
	v_and_b32_e32 v10, 15, v8
	v_lshrrev_b32_e32 v11, 2, v10
	v_sub_u32_e32 v11, 0, v11
	v_and_b32_e32 v11, 3, v11
	v_xor_b32_e32 v11, v9, v11
	v_lshlrev_b32_e32 v6, 6, v10
	v_lshl_add_u32 v6, v11, 4, v6
	s_lshr_b32 vcc_lo, s23, 1
	s_mul_i32 vcc_lo, vcc_lo, 0x3000
	s_and_b32 vcc_hi, s23, 1
	s_mul_i32 vcc_hi, vcc_hi, 0x3000
	s_add_u32 vcc_hi, vcc_hi, 0x800
	v_add_u32_e32 v7, vcc_hi, v6
	v_add_u32_e32 v6, vcc_lo, v6
	s_mul_i32 s22, s23, 0x1800
	v_writelane_b32 v253, s22, 6
	v_writelane_b32 v253, 0, 5
	v_readlane_b32 vcc_lo, v253, 0
	v_readlane_b32 vcc_hi, v253, 1
	s_lshl_b32 s23, s8, 18
	s_nop 1
	s_add_u32 s98, vcc_lo, s23
	s_addc_u32 s99, vcc_hi, 0
	s_sub_u32 s98, s98, 0x1000
	s_subb_u32 s99, s99, 0
	v_readlane_b32 vcc_lo, v253, 2
	v_readlane_b32 vcc_hi, v253, 3
	s_lshl_b32 s23, s9, 14
	s_nop 1
	s_add_u32 s100, vcc_lo, s23
	s_addc_u32 s101, vcc_hi, 0
	s_sub_u32 s100, s100, 0x1000
	s_subb_u32 s101, s101, 0
	s_add_u32 m0, s21, s22
	s_nop 0
	global_load_lds_dwordx4 v0, s[98:99]
	global_load_lds_dwordx4 v1, s[98:99] offset:1024
	global_load_lds_dwordx4 v2, s[100:101] offset:2048
	global_load_lds_dwordx4 v3, s[100:101] offset:3072
	s_add_u32 m0, m0, 0x1000
	s_nop 0
	global_load_lds_dwordx4 v4, s[100:101]
	global_load_lds_dwordx4 v5, s[100:101] offset:1024
	s_add_u32 s98, s98, 64
	s_addc_u32 s99, s99, 0
	s_add_u32 s100, s100, 0x10000
	s_addc_u32 s101, s101, 0
	s_add_u32 s23, s21, 0x6000
	s_cmp_eq_u32 s23, 0x12000
	s_cselect_b32 s23, 0, s23
	s_add_u32 m0, s23, s22
	s_nop 0
	global_load_lds_dwordx4 v0, s[98:99]
	global_load_lds_dwordx4 v1, s[98:99] offset:1024
	global_load_lds_dwordx4 v2, s[100:101] offset:2048
	global_load_lds_dwordx4 v3, s[100:101] offset:3072
	s_add_u32 m0, m0, 0x1000
	s_nop 0
	global_load_lds_dwordx4 v4, s[100:101]
	global_load_lds_dwordx4 v5, s[100:101] offset:1024
	s_add_u32 s98, s98, 64
	s_addc_u32 s99, s99, 0
	s_add_u32 s100, s100, 0x10000
	s_addc_u32 s101, s101, 0
	s_add_u32 s23, s23, 0x6000
	s_cmp_eq_u32 s23, 0x12000
	s_cselect_b32 s23, 0, s23
	s_add_u32 m0, s23, s22
	s_nop 0
	global_load_lds_dwordx4 v0, s[98:99]
	global_load_lds_dwordx4 v1, s[98:99] offset:1024
	global_load_lds_dwordx4 v2, s[100:101] offset:2048
	global_load_lds_dwordx4 v3, s[100:101] offset:3072
	s_add_u32 m0, m0, 0x1000
	s_nop 0
	global_load_lds_dwordx4 v4, s[100:101]
	global_load_lds_dwordx4 v5, s[100:101] offset:1024
	s_add_u32 s98, s98, 64
	s_addc_u32 s99, s99, 0
	s_add_u32 s100, s100, 0x10000
	s_addc_u32 s101, s101, 0

; DI f32x4 mfma(bf16x8 a, bf16x8 b, f32x4 c) { return __builtin_amdgcn_mfma_f32_16x16x32_bf16(a, b, c, 0, 0, 0); }
; #define G_LOAD(PA, PB, STEP) do { _Pragma("unroll") for (int i_ = 0; i_ < 2; ++i_) ra[i_] = *(const u32x4*)((PA) + (size_t)(64 * i_) * K + (STEP) * 32); \
;         _Pragma("unroll") for (int i_ = 0; i_ < 4; ++i_) rb[i_] = *(const u32x4*)((PB) + (size_t)(64 * i_) * K + (STEP) * 32); } while (0)
; #define G_STORE(BUF) do { _Pragma("unroll") for (int i_ = 0; i_ < 2; ++i_) *(u32x4*)(sA + (BUF) * 128 * 40 + (lrow + 64 * i_) * 40 + lcc * 8) = ra[i_]; \
;         _Pragma("unroll") for (int i_ = 0; i_ < 4; ++i_) *(u32x4*)(sB + (BUF) * 256 * 40 + (lrow + 64 * i_) * 40 + lcc * 8) = rb[i_]; } while (0)
; template <int EPI> ...
;     ...
;         for (int kt = 0; kt < nk; ++kt) {
;             const int buf = kt & 1;
;             const bf16_t* a_ = sA + buf * 128 * 40 + (wr * 64 + fr) * 40 + fq * 8;
;             const bf16_t* b_ = sB + buf * 256 * 40 + (wc * 128 + fr) * 40 + fq * 8;
;             bf16x8 af[4];
; #pragma unroll
;             for (int i = 0; i < 4; ++i) af[i] = *(const bf16x8*)(a_ + i * 16 * 40);
; #pragma unroll
;             for (int jh = 0; jh < 2; ++jh) {
;                 bf16x8 bfr[4];
; #pragma unroll
;                 for (int j = 0; j < 4; ++j) bfr[j] = *(const bf16x8*)(b_ + (jh * 4 + j) * 16 * 40);
; #pragma unroll
;                 for (int i = 0; i < 4; ++i)
; #pragma unroll
;                     for (int j = 0; j < 4; ++j) acc[i][jh * 4 + j] = mfma(bfr[j], af[i], acc[i][jh * 4 + j]);
;             }
;             G_STORE(buf ^ 1);
;             {
;                 const bool cur = kt + 2 < nk;
;                 const bf16_t* pa = cur ? Ag : An; const bf16_t* pb = cur ? Bg : Bn;
;                 const int st = cur ? kt + 2 : kt + 2 - nk;
;                 G_LOAD(pa, pb, st);
;             }
;             __syncthreads();
;         }
.Lg691_swret:
	s_add_u32 m0, s21, s22
	v_mfma_f32_16x16x32_bf16 v[132:135], v[204:207], v[10:13], v[132:135]
	global_load_lds_dwordx4 v0, s[98:99]
	v_mfma_f32_16x16x32_bf16 v[128:131], v[232:235], v[10:13], v[128:131]
	v_mfma_f32_16x16x32_bf16 v[124:127], v[236:239], v[10:13], v[124:127]
	global_load_lds_dwordx4 v1, s[98:99] offset:1024
	v_mfma_f32_16x16x32_bf16 v[120:123], v[240:243], v[10:13], v[120:123]
	ds_read_b128 v[10:13], v8
	v_mfma_f32_16x16x32_bf16 v[100:103], v[204:207], v[14:17], v[100:103]
	global_load_lds_dwordx4 v2, s[100:101] offset:2048
	v_mfma_f32_16x16x32_bf16 v[96:99], v[232:235], v[14:17], v[96:99]
	v_mfma_f32_16x16x32_bf16 v[92:95], v[236:239], v[14:17], v[92:95]
	global_load_lds_dwordx4 v3, s[100:101] offset:3072
	v_mfma_f32_16x16x32_bf16 v[88:91], v[240:243], v[14:17], v[88:91]
	ds_read_b128 v[14:17], v8 offset:1024
	v_mfma_f32_16x16x32_bf16 v[68:71], v[204:207], v[18:21], v[68:71]
	s_add_u32 m0, m0, 0x1000
	v_mfma_f32_16x16x32_bf16 v[64:67], v[232:235], v[18:21], v[64:67]
	global_load_lds_dwordx4 v4, s[100:101]
	v_mfma_f32_16x16x32_bf16 v[60:63], v[236:239], v[18:21], v[60:63]
	v_mfma_f32_16x16x32_bf16 v[56:59], v[240:243], v[18:21], v[56:59]
	ds_read_b128 v[18:21], v8 offset:6144
	v_mfma_f32_16x16x32_bf16 v[36:39], v[204:207], v[154:157], v[36:39]
	global_load_lds_dwordx4 v5, s[100:101] offset:1024
	v_mfma_f32_16x16x32_bf16 v[32:35], v[232:235], v[154:157], v[32:35]
	v_mfma_f32_16x16x32_bf16 v[28:31], v[236:239], v[154:157], v[28:31]
	v_mfma_f32_16x16x32_bf16 v[24:27], v[240:243], v[154:157], v[24:27]
	ds_read_b128 v[154:157], v8 offset:7168
	ds_read_b128 v[204:207], v9 offset:6144
	ds_read_b128 v[232:235], v9 offset:7168
	ds_read_b128 v[236:239], v9 offset:8192
	ds_read_b128 v[240:243], v9 offset:9216
	s_add_u32 s98, s98, 64
	s_addc_u32 s99, s99, 0
	s_add_u32 s100, s100, 0x10000
	s_addc_u32 s101, s101, 0
	s_add_u32 s21, s21, 0x6000
	s_cmp_eq_u32 s21, 0x12000
	s_cselect_b32 s21, 0, s21
	s_add_u32 s20, s20, 1
	s_cmp_lt_u32 s20, 31
	s_cbranch_scc1 .Lg691_top
	s_waitcnt lgkmcnt(4)
	v_mfma_f32_16x16x32_bf16 v[148:151], v[174:177], v[10:13], v[148:151]
	v_mfma_f32_16x16x32_bf16 v[116:119], v[174:177], v[14:17], v[116:119]
	v_mfma_f32_16x16x32_bf16 v[84:87], v[174:177], v[18:21], v[84:87]
	v_mfma_f32_16x16x32_bf16 v[52:55], v[174:177], v[154:157], v[52:55]
	v_mfma_f32_16x16x32_bf16 v[144:147], v[192:195], v[10:13], v[144:147]
	v_mfma_f32_16x16x32_bf16 v[112:115], v[192:195], v[14:17], v[112:115]
	v_mfma_f32_16x16x32_bf16 v[80:83], v[192:195], v[18:21], v[80:83]
	v_mfma_f32_16x16x32_bf16 v[48:51], v[192:195], v[154:157], v[48:51]
	v_mfma_f32_16x16x32_bf16 v[140:143], v[196:199], v[10:13], v[140:143]
	v_mfma_f32_16x16x32_bf16 v[108:111], v[196:199], v[14:17], v[108:111]
	v_mfma_f32_16x16x32_bf16 v[76:79], v[196:199], v[18:21], v[76:79]
	v_mfma_f32_16x16x32_bf16 v[44:47], v[196:199], v[154:157], v[44:47]
	v_mfma_f32_16x16x32_bf16 v[136:139], v[200:203], v[10:13], v[136:139]
	v_mfma_f32_16x16x32_bf16 v[104:107], v[200:203], v[14:17], v[104:107]
	v_mfma_f32_16x16x32_bf16 v[72:75], v[200:203], v[18:21], v[72:75]
	v_mfma_f32_16x16x32_bf16 v[40:43], v[200:203], v[154:157], v[40:43]
	s_waitcnt vmcnt(6)
	s_waitcnt lgkmcnt(0)
	s_barrier
	s_add_u32 m0, s21, s22
	v_mfma_f32_16x16x32_bf16 v[132:135], v[204:207], v[10:13], v[132:135]
	global_load_lds_dwordx4 v0, s[98:99]
	v_mfma_f32_16x16x32_bf16 v[128:131], v[232:235], v[10:13], v[128:131]
	v_mfma_f32_16x16x32_bf16 v[124:127], v[236:239], v[10:13], v[124:127]
	global_load_lds_dwordx4 v1, s[98:99] offset:1024
	v_mfma_f32_16x16x32_bf16 v[120:123], v[240:243], v[10:13], v[120:123]
	v_mfma_f32_16x16x32_bf16 v[100:103], v[204:207], v[14:17], v[100:103]
	global_load_lds_dwordx4 v2, s[100:101] offset:2048
	v_mfma_f32_16x16x32_bf16 v[96:99], v[232:235], v[14:17], v[96:99]
	v_mfma_f32_16x16x32_bf16 v[92:95], v[236:239], v[14:17], v[92:95]
	global_load_lds_dwordx4 v3, s[100:101] offset:3072
	v_mfma_f32_16x16x32_bf16 v[88:91], v[240:243], v[14:17], v[88:91]
	v_mfma_f32_16x16x32_bf16 v[68:71], v[204:207], v[18:21], v[68:71]
	s_add_u32 m0, m0, 0x1000
	v_mfma_f32_16x16x32_bf16 v[64:67], v[232:235], v[18:21], v[64:67]
	global_load_lds_dwordx4 v4, s[100:101]
	v_mfma_f32_16x16x32_bf16 v[60:63], v[236:239], v[18:21], v[60:63]
	v_mfma_f32_16x16x32_bf16 v[56:59], v[240:243], v[18:21], v[56:59]
	v_mfma_f32_16x16x32_bf16 v[36:39], v[204:207], v[154:157], v[36:39]
	global_load_lds_dwordx4 v5, s[100:101] offset:1024
	v_mfma_f32_16x16x32_bf16 v[32:35], v[232:235], v[154:157], v[32:35]
	v_mfma_f32_16x16x32_bf16 v[28:31], v[236:239], v[154:157], v[28:31]
	v_mfma_f32_16x16x32_bf16 v[24:27], v[240:243], v[154:157], v[24:27]
	s_add_u32 s98, s98, 64
	s_addc_u32 s99, s99, 0
	s_add_u32 s100, s100, 0x10000
	s_addc_u32 s101, s101, 0
	s_add_u32 s21, s21, 0x6000
	s_cmp_eq_u32 s21, 0x12000
	s_cselect_b32 s21, 0, s21
	s_add_u32 s20, s20, 1
	s_branch .Lg691_end
; DI unsigned pk2(float lo, float hi) { f32x2 v = {lo, hi}; bf16x2_t r = __builtin_convertvector(v, bf16x2_t); return __builtin_bit_cast(unsigned, r); }
; #define G_LOAD(PA, PB, STEP) do { _Pragma("unroll") for (int i_ = 0; i_ < 2; ++i_) ra[i_] = *(const u32x4*)((PA) + (size_t)(64 * i_) * K + (STEP) * 32); \
;         _Pragma("unroll") for (int i_ = 0; i_ < 4; ++i_) rb[i_] = *(const u32x4*)((PB) + (size_t)(64 * i_) * K + (STEP) * 32); } while (0)
; template <int EPI> ...
;     ...
;                 const bf16_t* pa = cur ? Ag : An; const bf16_t* pb = cur ? Bg : Bn;
;                 const int st = cur ? kt + 2 : kt + 2 - nk;
;                 G_LOAD(pa, pb, st);
;             }
;     ...
;                 } else {
;                     *(f32x4*)(xout + (size_t)m * Nn + n0) = v0;
;                     *(f32x4*)(xout + (size_t)m * Nn + n0 + 4) = v1;
;                     if (hb) {
;                         const f32x4 g0 = *(const f32x4*)(gn + n0), g1 = *(const f32x4*)(gn + n0 + 4);
;                         u32x4 o4; o4[0] = pk2(v0[0] * g0[0], v0[1] * g0[1]); o4[1] = pk2(v0[2] * g0[2], v0[3] * g0[3]);
;                         o4[2] = pk2(v1[0] * g1[0], v1[1] * g1[1]); o4[3] = pk2(v1[2] * g1[2], v1[3] * g1[3]);
;                         *(u32x4*)(hb + (size_t)m * Nn + n0) = o4;
;                         sq += v0[0] * v0[0] + v0[1] * v0[1] + v0[2] * v0[2] + v0[3] * v0[3] + v1[0] * v1[0] + v1[1] * v1[1] + v1[2] * v1[2] + v1[3] * v1[3];
;                     }
.Lg691_sw:
	v_readlane_b32 vcc_lo, v253, 0
	v_readlane_b32 vcc_hi, v253, 1
	s_lshl_b32 s23, s17, 18
	s_nop 1
	s_add_u32 s98, vcc_lo, s23
	s_addc_u32 s99, vcc_hi, 0
	s_sub_u32 s98, s98, 0x1000
	s_subb_u32 s99, s99, 0
	v_readlane_b32 vcc_lo, v253, 2
	v_readlane_b32 vcc_hi, v253, 3
	s_lshl_b32 s23, s19, 14
	s_nop 1
	s_add_u32 s100, vcc_lo, s23
	s_addc_u32 s101, vcc_hi, 0
	s_sub_u32 s100, s100, 0x1000
	s_subb_u32 s101, s101, 0
	s_branch .Lg691_swret
.Lg691_end:
	s_setprio 0
	v_writelane_b32 v253, s21, 4
	v_readlane_b32 s52, v251, 34
	v_readlane_b32 s53, v251, 35
	v_readlane_b32 s54, v251, 36
	v_readlane_b32 s55, v251, 37
	v_readlane_b32 s56, v251, 38
	v_readlane_b32 s57, v251, 39
	v_readlane_b32 s58, v251, 40
	v_readlane_b32 s59, v251, 41
	v_readlane_b32 s60, v251, 42
	v_readlane_b32 s61, v251, 43
	v_readlane_b32 s62, v251, 44
	v_readlane_b32 s63, v251, 45
	v_readlane_b32 s64, v251, 46
	v_readlane_b32 s65, v251, 47
	v_readlane_b32 s66, v251, 48
	v_readlane_b32 s67, v251, 49
	v_or_b32_e32 v185, s16, v183
	v_lshl_add_u64 v[164:165], s[56:57], 0, v[164:165]
	v_readlane_b32 s52, v251, 0
	v_lshlrev_b64 v[174:175], 11, v[158:159]
	v_readlane_b32 s66, v251, 14
	v_readlane_b32 s67, v251, 15
	v_lshlrev_b32_e32 v188, 2, v185
	v_lshl_add_u64 v[176:177], v[164:165], 0, v[188:189]
	v_lshl_add_u64 v[174:175], s[66:67], 0, v[174:175]
	s_and_b64 vcc, exec, s[24:25]
	v_lshlrev_b32_e32 v164, 1, v185
	v_readlane_b32 s53, v251, 1
	v_readlane_b32 s54, v251, 2
	v_readlane_b32 s55, v251, 3
	v_readlane_b32 s56, v251, 4
	v_readlane_b32 s57, v251, 5
	v_readlane_b32 s58, v251, 6
	v_readlane_b32 s59, v251, 7
	v_readlane_b32 s60, v251, 8
	v_readlane_b32 s61, v251, 9
	v_readlane_b32 s62, v251, 10
	v_readlane_b32 s63, v251, 11
	v_readlane_b32 s64, v251, 12
	v_readlane_b32 s65, v251, 13
	global_store_dwordx4 v[176:177], v[148:151], off
	global_store_dwordx4 v[176:177], v[144:147], off offset:16
	s_cbranch_vccz .LBB0_694
	global_load_dwordx4 v[192:195], v188, s[12:13] offset:16
	global_load_dwordx4 v[196:199], v188, s[12:13]
	v_mov_b32_e32 v165, v189
	s_waitcnt vmcnt(1)
	v_pk_mul_f32 v[192:193], v[144:145], v[192:193]
	s_waitcnt vmcnt(0)
	v_pk_mul_f32 v[196:197], v[148:149], v[196:197]
	v_pk_mul_f32 v[148:149], v[148:149], v[148:149]
	v_pk_mul_f32 v[186:187], v[150:151], v[198:199]
	v_pk_mul_f32 v[150:151], v[150:151], v[150:151]
	v_add_f32_e32 v148, v148, v149
	v_add_f32_e32 v148, v150, v148
	v_pk_mul_f32 v[144:145], v[144:145], v[144:145]
	v_add_f32_e32 v148, v151, v148
	v_add_f32_e32 v144, v144, v148
	v_cvt_pk_bf16_f32 v196, v196, v197
	v_cvt_pk_bf16_f32 v197, v186, v187
	v_pk_mul_f32 v[186:187], v[146:147], v[194:195]
	v_pk_mul_f32 v[146:147], v[146:147], v[146:147]
	v_add_f32_e32 v144, v145, v144
	v_add_f32_e32 v144, v146, v144
	v_cvt_pk_bf16_f32 v198, v192, v193
	v_cvt_pk_bf16_f32 v199, v186, v187
	v_lshl_add_u64 v[186:187], v[174:175], 0, v[164:165]
	v_add_f32_e32 v144, v147, v144
	global_store_dwordx4 v[186:187], v[196:199], off
	s_branch .LBB0_695

; DI f32x4 mfma(bf16x8 a, bf16x8 b, f32x4 c) { return __builtin_amdgcn_mfma_f32_16x16x32_bf16(a, b, c, 0, 0, 0); }
; #define G_LOAD(PA, PB, STEP) do { _Pragma("unroll") for (int i_ = 0; i_ < 2; ++i_) ra[i_] = *(const u32x4*)((PA) + (size_t)(64 * i_) * K + (STEP) * 32); \
;         _Pragma("unroll") for (int i_ = 0; i_ < 4; ++i_) rb[i_] = *(const u32x4*)((PB) + (size_t)(64 * i_) * K + (STEP) * 32); } while (0)
; #define G_STORE(BUF) do { _Pragma("unroll") for (int i_ = 0; i_ < 2; ++i_) *(u32x4*)(sA + (BUF) * 128 * 40 + (lrow + 64 * i_) * 40 + lcc * 8) = ra[i_]; \
;         _Pragma("unroll") for (int i_ = 0; i_ < 4; ++i_) *(u32x4*)(sB + (BUF) * 256 * 40 + (lrow + 64 * i_) * 40 + lcc * 8) = rb[i_]; } while (0)
; template <int EPI> ...
;     ...
;     const int idx0 = blockIdx.x >> 3;
;     if (idx0 < perX) {
;         int mt0, nt0; tile_of(idx0, mt0, nt0);
;         const bf16_t* A0 = A + (size_t)(mt0 * 128 + lrow) * K + lcc * 8;
;         const bf16_t* B0 = Bt + (size_t)(nt0 * 256 + lrowp) * K + lcc * 8;
;         G_LOAD(A0, B0, 0);
;         G_STORE(0);
;         G_LOAD(A0, B0, 1);
;         __syncthreads();
;     }
;     ...
;         for (int kt = 0; kt < nk; ++kt) {
;             const int buf = kt & 1;
;             const bf16_t* a_ = sA + buf * 128 * 40 + (wr * 64 + fr) * 40 + fq * 8;
;             const bf16_t* b_ = sB + buf * 256 * 40 + (wc * 128 + fr) * 40 + fq * 8;
;             bf16x8 af[4];
; #pragma unroll
;             for (int i = 0; i < 4; ++i) af[i] = *(const bf16x8*)(a_ + i * 16 * 40);
; #pragma unroll
;             for (int jh = 0; jh < 2; ++jh) {
;                 bf16x8 bfr[4];
; #pragma unroll
;                 for (int j = 0; j < 4; ++j) bfr[j] = *(const bf16x8*)(b_ + (jh * 4 + j) * 16 * 40);
; #pragma unroll
;                 for (int i = 0; i < 4; ++i)
; #pragma unroll
;                     for (int j = 0; j < 4; ++j) acc[i][jh * 4 + j] = mfma(bfr[j], af[i], acc[i][jh * 4 + j]);
;             }
;             G_STORE(buf ^ 1);
;             {
;                 const bool cur = kt + 2 < nk;
;                 const bf16_t* pa = cur ? Ag : An; const bf16_t* pb = cur ? Bg : Bn;
;                 const int st = cur ? kt + 2 : kt + 2 - nk;
;                 G_LOAD(pa, pb, st);
;             }
.LBB0_778:
	v_readlane_b32 s16, v253, 4
	v_readlane_b32 s17, v253, 6
	v_readlane_b32 s18, v253, 5
	s_nop 3
	s_cmp_eq_u32 s18, 0
	s_cbranch_scc1 .Lg778_entry
	v_and_b32_e32 v8, 63, v210
	v_lshrrev_b32_e32 v9, 6, v210
	s_nop 0
	v_readfirstlane_b32 s18, v9
	v_lshrrev_b32_e32 v9, 4, v8
	v_sub_u32_e32 v10, 0, v9
	v_and_b32_e32 v10, 3, v10
	v_and_b32_e32 v11, 3, v8
	v_xor_b32_e32 v11, v11, v10
	v_lshrrev_b32_e32 v12, 2, v8
	v_lshlrev_b32_e32 v0, 11, v12
	v_lshl_add_u32 v0, v11, 4, v0
	s_lshl_b32 vcc_lo, s18, 16
	v_add_u32_e32 v0, vcc_lo, v0
	v_add_u32_e32 v0, 0x1000, v0
	v_add_u32_e32 v1, 0x7c00, v0
	v_and_b32_e32 v13, 3, v12
	v_lshl_add_u32 v13, v9, 3, v13
	v_lshlrev_b32_e32 v2, 6, v13
	v_lshl_add_u32 v2, v11, 4, v2
	s_lshl_b32 vcc_lo, s18, 12
	v_add_u32_e32 v2, vcc_lo, v2
	v_add_u32_e32 v2, 0x800, v2
	v_add_u32_e32 v3, 0xfffffd00, v2
	v_add_u32_e32 v4, 0x1000, v2
	v_add_u32_e32 v5, 0xd00, v2
	v_and_b32_e32 v10, 15, v8
	v_lshrrev_b32_e32 v11, 2, v10
	v_sub_u32_e32 v11, 0, v11
	v_and_b32_e32 v11, 3, v11
	v_xor_b32_e32 v11, v9, v11
	v_lshlrev_b32_e32 v6, 6, v10
	v_lshl_add_u32 v6, v11, 4, v6
	s_lshr_b32 vcc_lo, s18, 1
	s_mul_i32 vcc_lo, vcc_lo, 0x3000
	s_and_b32 vcc_hi, s18, 1
	s_mul_i32 vcc_hi, vcc_hi, 0x3000
	s_add_u32 vcc_hi, vcc_hi, 0x800
	v_add_u32_e32 v7, vcc_hi, v6
	v_add_u32_e32 v6, vcc_lo, v6
	s_mul_i32 s17, s18, 0x1800
	v_writelane_b32 v253, s17, 6
	v_writelane_b32 v253, 0, 5
	v_readlane_b32 vcc_lo, v253, 0
	v_readlane_b32 vcc_hi, v253, 1
	s_lshl_b32 s18, s7, 18
	s_nop 1
	s_add_u32 s98, vcc_lo, s18
	s_addc_u32 s99, vcc_hi, 0
	s_sub_u32 s98, s98, 0x1000
	s_subb_u32 s99, s99, 0
	v_readlane_b32 vcc_lo, v253, 2
	v_readlane_b32 vcc_hi, v253, 3
	s_lshl_b32 s18, s6, 14
	s_nop 1
	s_add_u32 s100, vcc_lo, s18
	s_addc_u32 s101, vcc_hi, 0
	s_sub_u32 s100, s100, 0x1000
	s_subb_u32 s101, s101, 0
	s_add_u32 m0, s16, s17
	s_nop 0
	global_load_lds_dwordx4 v0, s[98:99]
	global_load_lds_dwordx4 v1, s[98:99] offset:1024
	global_load_lds_dwordx4 v2, s[100:101] offset:2048
	global_load_lds_dwordx4 v3, s[100:101] offset:3072
	s_add_u32 m0, m0, 0x1000
	s_nop 0
	global_load_lds_dwordx4 v4, s[100:101]
	global_load_lds_dwordx4 v5, s[100:101] offset:1024
	s_add_u32 s98, s98, 64
	s_addc_u32 s99, s99, 0
	s_add_u32 s100, s100, 0x40000
	s_addc_u32 s101, s101, 0
	s_add_u32 s18, s16, 0x6000
	s_cmp_eq_u32 s18, 0x12000
	s_cselect_b32 s18, 0, s18
	s_add_u32 m0, s18, s17
	s_nop 0
	global_load_lds_dwordx4 v0, s[98:99]
	global_load_lds_dwordx4 v1, s[98:99] offset:1024
	global_load_lds_dwordx4 v2, s[100:101] offset:2048
	global_load_lds_dwordx4 v3, s[100:101] offset:3072
	s_add_u32 m0, m0, 0x1000
	s_nop 0
	global_load_lds_dwordx4 v4, s[100:101]
	global_load_lds_dwordx4 v5, s[100:101] offset:1024
	s_add_u32 s98, s98, 64
	s_addc_u32 s99, s99, 0
	s_add_u32 s100, s100, 0x40000
	s_addc_u32 s101, s101, 0
	s_add_u32 s18, s18, 0x6000
	s_cmp_eq_u32 s18, 0x12000
	s_cselect_b32 s18, 0, s18
	s_add_u32 m0, s18, s17
	s_nop 0
	global_load_lds_dwordx4 v0, s[98:99]
	global_load_lds_dwordx4 v1, s[98:99] offset:1024
	global_load_lds_dwordx4 v2, s[100:101] offset:2048
	global_load_lds_dwordx4 v3, s[100:101] offset:3072
	s_add_u32 m0, m0, 0x1000
	s_nop 0
	global_load_lds_dwordx4 v4, s[100:101]
	global_load_lds_dwordx4 v5, s[100:101] offset:1024
	s_add_u32 s98, s98, 64
	s_addc_u32 s99, s99, 0
	s_add_u32 s100, s100, 0x40000
	s_addc_u32 s101, s101, 0

; DI f32x4 mfma(bf16x8 a, bf16x8 b, f32x4 c) { return __builtin_amdgcn_mfma_f32_16x16x32_bf16(a, b, c, 0, 0, 0); }
; #define G_LOAD(PA, PB, STEP) do { _Pragma("unroll") for (int i_ = 0; i_ < 2; ++i_) ra[i_] = *(const u32x4*)((PA) + (size_t)(64 * i_) * K + (STEP) * 32); \
;         _Pragma("unroll") for (int i_ = 0; i_ < 4; ++i_) rb[i_] = *(const u32x4*)((PB) + (size_t)(64 * i_) * K + (STEP) * 32); } while (0)
; #define G_STORE(BUF) do { _Pragma("unroll") for (int i_ = 0; i_ < 2; ++i_) *(u32x4*)(sA + (BUF) * 128 * 40 + (lrow + 64 * i_) * 40 + lcc * 8) = ra[i_]; \
;         _Pragma("unroll") for (int i_ = 0; i_ < 4; ++i_) *(u32x4*)(sB + (BUF) * 256 * 40 + (lrow + 64 * i_) * 40 + lcc * 8) = rb[i_]; } while (0)
; template <int EPI> ...
;     ...
;         for (int kt = 0; kt < nk; ++kt) {
;             const int buf = kt & 1;
;             const bf16_t* a_ = sA + buf * 128 * 40 + (wr * 64 + fr) * 40 + fq * 8;
;             const bf16_t* b_ = sB + buf * 256 * 40 + (wc * 128 + fr) * 40 + fq * 8;
;             bf16x8 af[4];
; #pragma unroll
;             for (int i = 0; i < 4; ++i) af[i] = *(const bf16x8*)(a_ + i * 16 * 40);
; #pragma unroll
;             for (int jh = 0; jh < 2; ++jh) {
;                 bf16x8 bfr[4];
; #pragma unroll
;                 for (int j = 0; j < 4; ++j) bfr[j] = *(const bf16x8*)(b_ + (jh * 4 + j) * 16 * 40);
; #pragma unroll
;                 for (int i = 0; i < 4; ++i)
; #pragma unroll
;                     for (int j = 0; j < 4; ++j) acc[i][jh * 4 + j] = mfma(bfr[j], af[i], acc[i][jh * 4 + j]);
;             }
;             G_STORE(buf ^ 1);
;             {
;                 const bool cur = kt + 2 < nk;
;                 const bf16_t* pa = cur ? Ag : An; const bf16_t* pb = cur ? Bg : Bn;
;                 const int st = cur ? kt + 2 : kt + 2 - nk;
;                 G_LOAD(pa, pb, st);
;             }
;             __syncthreads();
;         }
;     ...
; #pragma unroll
;         for (int i = 0; i < 4; ++i) {
;             const int m = mt * 128 + wr * 64 + i * 16 + fr;
;             float rsc = 1.f;
;             if (EPI != 2 && rs_in) rsc = rsqrtf(rs_in[m] * (1.f / DM) + 1e-6f);
.Lg778_swret:
	s_add_u32 m0, s16, s17
	v_mfma_f32_16x16x32_bf16 v[132:135], v[192:195], v[10:13], v[132:135]
	global_load_lds_dwordx4 v0, s[98:99]
	v_mfma_f32_16x16x32_bf16 v[128:131], v[196:199], v[10:13], v[128:131]
	v_mfma_f32_16x16x32_bf16 v[124:127], v[200:203], v[10:13], v[124:127]
	global_load_lds_dwordx4 v1, s[98:99] offset:1024
	v_mfma_f32_16x16x32_bf16 v[120:123], v[204:207], v[10:13], v[120:123]
	ds_read_b128 v[10:13], v8
	v_mfma_f32_16x16x32_bf16 v[100:103], v[192:195], v[14:17], v[100:103]
	global_load_lds_dwordx4 v2, s[100:101] offset:2048
	v_mfma_f32_16x16x32_bf16 v[96:99], v[196:199], v[14:17], v[96:99]
	v_mfma_f32_16x16x32_bf16 v[92:95], v[200:203], v[14:17], v[92:95]
	global_load_lds_dwordx4 v3, s[100:101] offset:3072
	v_mfma_f32_16x16x32_bf16 v[88:91], v[204:207], v[14:17], v[88:91]
	ds_read_b128 v[14:17], v8 offset:1024
	v_mfma_f32_16x16x32_bf16 v[68:71], v[192:195], v[18:21], v[68:71]
	s_add_u32 m0, m0, 0x1000
	v_mfma_f32_16x16x32_bf16 v[64:67], v[196:199], v[18:21], v[64:67]
	global_load_lds_dwordx4 v4, s[100:101]
	v_mfma_f32_16x16x32_bf16 v[60:63], v[200:203], v[18:21], v[60:63]
	v_mfma_f32_16x16x32_bf16 v[56:59], v[204:207], v[18:21], v[56:59]
	ds_read_b128 v[18:21], v8 offset:6144
	v_mfma_f32_16x16x32_bf16 v[36:39], v[192:195], v[152:155], v[36:39]
	global_load_lds_dwordx4 v5, s[100:101] offset:1024
	v_mfma_f32_16x16x32_bf16 v[32:35], v[196:199], v[152:155], v[32:35]
	v_mfma_f32_16x16x32_bf16 v[28:31], v[200:203], v[152:155], v[28:31]
	v_mfma_f32_16x16x32_bf16 v[24:27], v[204:207], v[152:155], v[24:27]
	ds_read_b128 v[152:155], v8 offset:7168
	ds_read_b128 v[192:195], v9 offset:6144
	ds_read_b128 v[196:199], v9 offset:7168
	ds_read_b128 v[200:203], v9 offset:8192
	ds_read_b128 v[204:207], v9 offset:9216
	s_add_u32 s98, s98, 64
	s_addc_u32 s99, s99, 0
	s_add_u32 s100, s100, 0x40000
	s_addc_u32 s101, s101, 0
	s_add_u32 s16, s16, 0x6000
	s_cmp_eq_u32 s16, 0x12000
	s_cselect_b32 s16, 0, s16
	s_add_u32 s15, s15, 1
	s_cmp_lt_u32 s15, 31
	s_cbranch_scc1 .Lg778_top
	s_waitcnt lgkmcnt(4)
	v_mfma_f32_16x16x32_bf16 v[148:151], v[172:175], v[10:13], v[148:151]
	v_mfma_f32_16x16x32_bf16 v[116:119], v[172:175], v[14:17], v[116:119]
	v_mfma_f32_16x16x32_bf16 v[84:87], v[172:175], v[18:21], v[84:87]
	v_mfma_f32_16x16x32_bf16 v[52:55], v[172:175], v[152:155], v[52:55]
	v_mfma_f32_16x16x32_bf16 v[144:147], v[176:179], v[10:13], v[144:147]
	v_mfma_f32_16x16x32_bf16 v[112:115], v[176:179], v[14:17], v[112:115]
	v_mfma_f32_16x16x32_bf16 v[80:83], v[176:179], v[18:21], v[80:83]
	v_mfma_f32_16x16x32_bf16 v[48:51], v[176:179], v[152:155], v[48:51]
	v_mfma_f32_16x16x32_bf16 v[140:143], v[180:183], v[10:13], v[140:143]
	v_mfma_f32_16x16x32_bf16 v[108:111], v[180:183], v[14:17], v[108:111]
	v_mfma_f32_16x16x32_bf16 v[76:79], v[180:183], v[18:21], v[76:79]
	v_mfma_f32_16x16x32_bf16 v[44:47], v[180:183], v[152:155], v[44:47]
	v_mfma_f32_16x16x32_bf16 v[136:139], v[184:187], v[10:13], v[136:139]
	v_mfma_f32_16x16x32_bf16 v[104:107], v[184:187], v[14:17], v[104:107]
	v_mfma_f32_16x16x32_bf16 v[72:75], v[184:187], v[18:21], v[72:75]
	v_mfma_f32_16x16x32_bf16 v[40:43], v[184:187], v[152:155], v[40:43]
	s_waitcnt vmcnt(6)
	s_waitcnt lgkmcnt(0)
	s_barrier
	s_add_u32 m0, s16, s17
	v_mfma_f32_16x16x32_bf16 v[132:135], v[192:195], v[10:13], v[132:135]
	global_load_lds_dwordx4 v0, s[98:99]
	v_mfma_f32_16x16x32_bf16 v[128:131], v[196:199], v[10:13], v[128:131]
	v_mfma_f32_16x16x32_bf16 v[124:127], v[200:203], v[10:13], v[124:127]
	global_load_lds_dwordx4 v1, s[98:99] offset:1024
	v_mfma_f32_16x16x32_bf16 v[120:123], v[204:207], v[10:13], v[120:123]
	v_mfma_f32_16x16x32_bf16 v[100:103], v[192:195], v[14:17], v[100:103]
	global_load_lds_dwordx4 v2, s[100:101] offset:2048
	v_mfma_f32_16x16x32_bf16 v[96:99], v[196:199], v[14:17], v[96:99]
	v_mfma_f32_16x16x32_bf16 v[92:95], v[200:203], v[14:17], v[92:95]
	global_load_lds_dwordx4 v3, s[100:101] offset:3072
	v_mfma_f32_16x16x32_bf16 v[88:91], v[204:207], v[14:17], v[88:91]
	v_mfma_f32_16x16x32_bf16 v[68:71], v[192:195], v[18:21], v[68:71]
	s_add_u32 m0, m0, 0x1000
	v_mfma_f32_16x16x32_bf16 v[64:67], v[196:199], v[18:21], v[64:67]
	global_load_lds_dwordx4 v4, s[100:101]
	v_mfma_f32_16x16x32_bf16 v[60:63], v[200:203], v[18:21], v[60:63]
	v_mfma_f32_16x16x32_bf16 v[56:59], v[204:207], v[18:21], v[56:59]
	v_mfma_f32_16x16x32_bf16 v[36:39], v[192:195], v[152:155], v[36:39]
	global_load_lds_dwordx4 v5, s[100:101] offset:1024
	v_mfma_f32_16x16x32_bf16 v[32:35], v[196:199], v[152:155], v[32:35]
	v_mfma_f32_16x16x32_bf16 v[28:31], v[200:203], v[152:155], v[28:31]
	v_mfma_f32_16x16x32_bf16 v[24:27], v[204:207], v[152:155], v[24:27]
	s_add_u32 s98, s98, 64
	s_addc_u32 s99, s99, 0
	s_add_u32 s100, s100, 0x40000
	s_addc_u32 s101, s101, 0
	s_add_u32 s16, s16, 0x6000
	s_cmp_eq_u32 s16, 0x12000
	s_cselect_b32 s16, 0, s16
	s_add_u32 s15, s15, 1
	s_branch .Lg778_end
.Lg778_sw:
	v_readlane_b32 vcc_lo, v253, 0
	v_readlane_b32 vcc_hi, v253, 1
	s_lshl_b32 s18, s13, 18
	s_nop 1
	s_add_u32 s98, vcc_lo, s18
	s_addc_u32 s99, vcc_hi, 0
	s_sub_u32 s98, s98, 0x1000
	s_subb_u32 s99, s99, 0
	v_readlane_b32 vcc_lo, v253, 2
	v_readlane_b32 vcc_hi, v253, 3
	s_lshl_b32 s18, s14, 14
	s_nop 1
	s_add_u32 s100, vcc_lo, s18
	s_addc_u32 s101, vcc_hi, 0
	s_sub_u32 s100, s100, 0x1000
	s_subb_u32 s101, s101, 0
	s_branch .Lg778_swret
.Lg778_end:
	s_setprio 0
	v_writelane_b32 v253, s16, 4
	v_lshl_add_u32 v154, s7, 7, v167
	v_ashrrev_i32_e32 v155, 31, v154
	v_mov_b32_e32 v162, 1.0
	s_and_b64 vcc, exec, s[20:21]
	v_lshl_add_u64 v[160:161], v[154:155], 2, s[10:11]
	v_mov_b32_e32 v164, 1.0
	s_cbranch_vccz .LBB0_781
	global_load_dword v152, v[160:161], off
	s_waitcnt vmcnt(0)
	v_fmamk_f32 v152, v152, 0x3a800000, v212
	v_mul_f32_e32 v153, 0x4b800000, v152
	v_cmp_gt_f32_e32 vcc, s28, v152
	s_nop 1
	v_cndmask_b32_e32 v152, v152, v153, vcc
	v_rsq_f32_e32 v152, v152
	s_nop 0
	v_mul_f32_e32 v153, 0x45800000, v152
	v_cndmask_b32_e32 v164, v152, v153, vcc

; DI f32x4 mfma(bf16x8 a, bf16x8 b, f32x4 c) { return __builtin_amdgcn_mfma_f32_16x16x32_bf16(a, b, c, 0, 0, 0); }
; #define G_LOAD(PA, PB, STEP) do { _Pragma("unroll") for (int i_ = 0; i_ < 2; ++i_) ra[i_] = *(const u32x4*)((PA) + (size_t)(64 * i_) * K + (STEP) * 32); \
;         _Pragma("unroll") for (int i_ = 0; i_ < 4; ++i_) rb[i_] = *(const u32x4*)((PB) + (size_t)(64 * i_) * K + (STEP) * 32); } while (0)
; #define G_STORE(BUF) do { _Pragma("unroll") for (int i_ = 0; i_ < 2; ++i_) *(u32x4*)(sA + (BUF) * 128 * 40 + (lrow + 64 * i_) * 40 + lcc * 8) = ra[i_]; \
;         _Pragma("unroll") for (int i_ = 0; i_ < 4; ++i_) *(u32x4*)(sB + (BUF) * 256 * 40 + (lrow + 64 * i_) * 40 + lcc * 8) = rb[i_]; } while (0)
; template <int EPI> ...
;     ...
;     const int idx0 = blockIdx.x >> 3;
;     if (idx0 < perX) {
;         int mt0, nt0; tile_of(idx0, mt0, nt0);
;         const bf16_t* A0 = A + (size_t)(mt0 * 128 + lrow) * K + lcc * 8;
;         const bf16_t* B0 = Bt + (size_t)(nt0 * 256 + lrowp) * K + lcc * 8;
;         G_LOAD(A0, B0, 0);
;         G_STORE(0);
;         G_LOAD(A0, B0, 1);
;         __syncthreads();
;     }
;     ...
;         for (int kt = 0; kt < nk; ++kt) {
;             const int buf = kt & 1;
;             const bf16_t* a_ = sA + buf * 128 * 40 + (wr * 64 + fr) * 40 + fq * 8;
;             const bf16_t* b_ = sB + buf * 256 * 40 + (wc * 128 + fr) * 40 + fq * 8;
;             bf16x8 af[4];
; #pragma unroll
;             for (int i = 0; i < 4; ++i) af[i] = *(const bf16x8*)(a_ + i * 16 * 40);
; #pragma unroll
;             for (int jh = 0; jh < 2; ++jh) {
;                 bf16x8 bfr[4];
; #pragma unroll
;                 for (int j = 0; j < 4; ++j) bfr[j] = *(const bf16x8*)(b_ + (jh * 4 + j) * 16 * 40);
; #pragma unroll
;                 for (int i = 0; i < 4; ++i)
; #pragma unroll
;                     for (int j = 0; j < 4; ++j) acc[i][jh * 4 + j] = mfma(bfr[j], af[i], acc[i][jh * 4 + j]);
;             }
;             G_STORE(buf ^ 1);
;             {
;                 const bool cur = kt + 2 < nk;
;                 const bf16_t* pa = cur ? Ag : An; const bf16_t* pb = cur ? Bg : Bn;
;                 const int st = cur ? kt + 2 : kt + 2 - nk;
;                 G_LOAD(pa, pb, st);
;             }
.LBB0_843:
	v_readlane_b32 s15, v253, 4
	v_readlane_b32 s16, v253, 6
	v_readlane_b32 s17, v253, 5
	s_nop 3
	s_cmp_eq_u32 s17, 0
	s_cbranch_scc1 .Lg843_entry
	v_and_b32_e32 v8, 63, v210
	v_lshrrev_b32_e32 v9, 6, v210
	s_nop 0
	v_readfirstlane_b32 s17, v9
	v_lshrrev_b32_e32 v9, 4, v8
	v_sub_u32_e32 v10, 0, v9
	v_and_b32_e32 v10, 3, v10
	v_and_b32_e32 v11, 3, v8
	v_xor_b32_e32 v11, v11, v10
	v_lshrrev_b32_e32 v12, 2, v8
	v_lshlrev_b32_e32 v0, 13, v12
	v_lshl_add_u32 v0, v11, 4, v0
	s_lshl_b32 vcc_lo, s17, 18
	v_add_u32_e32 v0, vcc_lo, v0
	v_add_u32_e32 v0, 0x1000, v0
	v_add_u32_e32 v1, 0x1fc00, v0
	v_and_b32_e32 v13, 3, v12
	v_lshl_add_u32 v13, v9, 3, v13
	v_lshlrev_b32_e32 v2, 6, v13
	v_lshl_add_u32 v2, v11, 4, v2
	s_lshl_b32 vcc_lo, s17, 12
	v_add_u32_e32 v2, vcc_lo, v2
	v_add_u32_e32 v2, 0x800, v2
	v_add_u32_e32 v3, 0xfffffd00, v2
	v_add_u32_e32 v4, 0x1000, v2
	v_add_u32_e32 v5, 0xd00, v2
	v_and_b32_e32 v10, 15, v8
	v_lshrrev_b32_e32 v11, 2, v10
	v_sub_u32_e32 v11, 0, v11
	v_and_b32_e32 v11, 3, v11
	v_xor_b32_e32 v11, v9, v11
	v_lshlrev_b32_e32 v6, 6, v10
	v_lshl_add_u32 v6, v11, 4, v6
	s_lshr_b32 vcc_lo, s17, 1
	s_mul_i32 vcc_lo, vcc_lo, 0x3000
	s_and_b32 vcc_hi, s17, 1
	s_mul_i32 vcc_hi, vcc_hi, 0x3000
	s_add_u32 vcc_hi, vcc_hi, 0x800
	v_add_u32_e32 v7, vcc_hi, v6
	v_add_u32_e32 v6, vcc_lo, v6
	s_mul_i32 s16, s17, 0x1800
	v_writelane_b32 v253, s16, 6
	v_writelane_b32 v253, 0, 5
	v_readlane_b32 vcc_lo, v253, 0
	v_readlane_b32 vcc_hi, v253, 1
	s_lshl_b32 s17, s9, 20
	s_nop 1
	s_add_u32 s98, vcc_lo, s17
	s_addc_u32 s99, vcc_hi, 0
	s_sub_u32 s98, s98, 0x1000
	s_subb_u32 s99, s99, 0
	v_readlane_b32 vcc_lo, v253, 2
	v_readlane_b32 vcc_hi, v253, 3
	s_lshl_b32 s17, s10, 14
	s_nop 1
	s_add_u32 s100, vcc_lo, s17
	s_addc_u32 s101, vcc_hi, 0
	s_sub_u32 s100, s100, 0x1000
	s_subb_u32 s101, s101, 0
	s_add_u32 m0, s15, s16
	s_nop 0
	global_load_lds_dwordx4 v0, s[98:99]
	global_load_lds_dwordx4 v1, s[98:99] offset:1024
	global_load_lds_dwordx4 v2, s[100:101] offset:2048
	global_load_lds_dwordx4 v3, s[100:101] offset:3072
	s_add_u32 m0, m0, 0x1000
	s_nop 0
	global_load_lds_dwordx4 v4, s[100:101]
	global_load_lds_dwordx4 v5, s[100:101] offset:1024
	s_add_u32 s98, s98, 64
	s_addc_u32 s99, s99, 0
	s_add_u32 s100, s100, 0x10000
	s_addc_u32 s101, s101, 0
	s_add_u32 s17, s15, 0x6000
	s_cmp_eq_u32 s17, 0x12000
	s_cselect_b32 s17, 0, s17
	s_add_u32 m0, s17, s16
	s_nop 0
	global_load_lds_dwordx4 v0, s[98:99]
	global_load_lds_dwordx4 v1, s[98:99] offset:1024
	global_load_lds_dwordx4 v2, s[100:101] offset:2048
	global_load_lds_dwordx4 v3, s[100:101] offset:3072
	s_add_u32 m0, m0, 0x1000
	s_nop 0
	global_load_lds_dwordx4 v4, s[100:101]
	global_load_lds_dwordx4 v5, s[100:101] offset:1024
	s_add_u32 s98, s98, 64
	s_addc_u32 s99, s99, 0
	s_add_u32 s100, s100, 0x10000
	s_addc_u32 s101, s101, 0
	s_add_u32 s17, s17, 0x6000
	s_cmp_eq_u32 s17, 0x12000
	s_cselect_b32 s17, 0, s17
	s_add_u32 m0, s17, s16
	s_nop 0
	global_load_lds_dwordx4 v0, s[98:99]
	global_load_lds_dwordx4 v1, s[98:99] offset:1024
	global_load_lds_dwordx4 v2, s[100:101] offset:2048
	global_load_lds_dwordx4 v3, s[100:101] offset:3072
	s_add_u32 m0, m0, 0x1000
	s_nop 0
	global_load_lds_dwordx4 v4, s[100:101]
	global_load_lds_dwordx4 v5, s[100:101] offset:1024
	s_add_u32 s98, s98, 64
	s_addc_u32 s99, s99, 0
	s_add_u32 s100, s100, 0x10000
	s_addc_u32 s101, s101, 0

; DI f32x4 mfma(bf16x8 a, bf16x8 b, f32x4 c) { return __builtin_amdgcn_mfma_f32_16x16x32_bf16(a, b, c, 0, 0, 0); }
; #define G_LOAD(PA, PB, STEP) do { _Pragma("unroll") for (int i_ = 0; i_ < 2; ++i_) ra[i_] = *(const u32x4*)((PA) + (size_t)(64 * i_) * K + (STEP) * 32); \
;         _Pragma("unroll") for (int i_ = 0; i_ < 4; ++i_) rb[i_] = *(const u32x4*)((PB) + (size_t)(64 * i_) * K + (STEP) * 32); } while (0)
; #define G_STORE(BUF) do { _Pragma("unroll") for (int i_ = 0; i_ < 2; ++i_) *(u32x4*)(sA + (BUF) * 128 * 40 + (lrow + 64 * i_) * 40 + lcc * 8) = ra[i_]; \
;         _Pragma("unroll") for (int i_ = 0; i_ < 4; ++i_) *(u32x4*)(sB + (BUF) * 256 * 40 + (lrow + 64 * i_) * 40 + lcc * 8) = rb[i_]; } while (0)
; template <int EPI> ...
;     ...
;         for (int kt = 0; kt < nk; ++kt) {
;             const int buf = kt & 1;
;             const bf16_t* a_ = sA + buf * 128 * 40 + (wr * 64 + fr) * 40 + fq * 8;
;             const bf16_t* b_ = sB + buf * 256 * 40 + (wc * 128 + fr) * 40 + fq * 8;
;             bf16x8 af[4];
; #pragma unroll
;             for (int i = 0; i < 4; ++i) af[i] = *(const bf16x8*)(a_ + i * 16 * 40);
; #pragma unroll
;             for (int jh = 0; jh < 2; ++jh) {
;                 bf16x8 bfr[4];
; #pragma unroll
;                 for (int j = 0; j < 4; ++j) bfr[j] = *(const bf16x8*)(b_ + (jh * 4 + j) * 16 * 40);
; #pragma unroll
;                 for (int i = 0; i < 4; ++i)
; #pragma unroll
;                     for (int j = 0; j < 4; ++j) acc[i][jh * 4 + j] = mfma(bfr[j], af[i], acc[i][jh * 4 + j]);
;             }
;             G_STORE(buf ^ 1);
;             {
;                 const bool cur = kt + 2 < nk;
;                 const bf16_t* pa = cur ? Ag : An; const bf16_t* pb = cur ? Bg : Bn;
;                 const int st = cur ? kt + 2 : kt + 2 - nk;
;                 G_LOAD(pa, pb, st);
;             }
;             __syncthreads();
;         }
.Lg843_swret:
	s_add_u32 m0, s15, s16
	v_mfma_f32_16x16x32_bf16 v[132:135], v[196:199], v[10:13], v[132:135]
	global_load_lds_dwordx4 v0, s[98:99]
	v_mfma_f32_16x16x32_bf16 v[128:131], v[200:203], v[10:13], v[128:131]
	v_mfma_f32_16x16x32_bf16 v[124:127], v[204:207], v[10:13], v[124:127]
	global_load_lds_dwordx4 v1, s[98:99] offset:1024
	v_mfma_f32_16x16x32_bf16 v[120:123], v[232:235], v[10:13], v[120:123]
	ds_read_b128 v[10:13], v8
	v_mfma_f32_16x16x32_bf16 v[100:103], v[196:199], v[14:17], v[100:103]
	global_load_lds_dwordx4 v2, s[100:101] offset:2048
	v_mfma_f32_16x16x32_bf16 v[96:99], v[200:203], v[14:17], v[96:99]
	v_mfma_f32_16x16x32_bf16 v[92:95], v[204:207], v[14:17], v[92:95]
	global_load_lds_dwordx4 v3, s[100:101] offset:3072
	v_mfma_f32_16x16x32_bf16 v[88:91], v[232:235], v[14:17], v[88:91]
	ds_read_b128 v[14:17], v8 offset:1024
	v_mfma_f32_16x16x32_bf16 v[68:71], v[196:199], v[18:21], v[68:71]
	s_add_u32 m0, m0, 0x1000
	v_mfma_f32_16x16x32_bf16 v[64:67], v[200:203], v[18:21], v[64:67]
	global_load_lds_dwordx4 v4, s[100:101]
	v_mfma_f32_16x16x32_bf16 v[60:63], v[204:207], v[18:21], v[60:63]
	v_mfma_f32_16x16x32_bf16 v[56:59], v[232:235], v[18:21], v[56:59]
	ds_read_b128 v[18:21], v8 offset:6144
	v_mfma_f32_16x16x32_bf16 v[36:39], v[196:199], v[154:157], v[36:39]
	global_load_lds_dwordx4 v5, s[100:101] offset:1024
	v_mfma_f32_16x16x32_bf16 v[32:35], v[200:203], v[154:157], v[32:35]
	v_mfma_f32_16x16x32_bf16 v[28:31], v[204:207], v[154:157], v[28:31]
	v_mfma_f32_16x16x32_bf16 v[24:27], v[232:235], v[154:157], v[24:27]
	ds_read_b128 v[154:157], v8 offset:7168
	ds_read_b128 v[196:199], v9 offset:6144
	ds_read_b128 v[200:203], v9 offset:7168
	ds_read_b128 v[204:207], v9 offset:8192
	ds_read_b128 v[232:235], v9 offset:9216
	s_add_u32 s98, s98, 64
	s_addc_u32 s99, s99, 0
	s_add_u32 s100, s100, 0x10000
	s_addc_u32 s101, s101, 0
	s_add_u32 s15, s15, 0x6000
	s_cmp_eq_u32 s15, 0x12000
	s_cselect_b32 s15, 0, s15
	s_add_u32 s14, s14, 1
	s_cmp_lt_u32 s14, 127
	s_cbranch_scc1 .Lg843_top
	s_waitcnt lgkmcnt(4)
	v_mfma_f32_16x16x32_bf16 v[148:151], v[174:177], v[10:13], v[148:151]
	v_mfma_f32_16x16x32_bf16 v[116:119], v[174:177], v[14:17], v[116:119]
	v_mfma_f32_16x16x32_bf16 v[84:87], v[174:177], v[18:21], v[84:87]
	v_mfma_f32_16x16x32_bf16 v[52:55], v[174:177], v[154:157], v[52:55]
	v_mfma_f32_16x16x32_bf16 v[144:147], v[178:181], v[10:13], v[144:147]
	v_mfma_f32_16x16x32_bf16 v[112:115], v[178:181], v[14:17], v[112:115]
	v_mfma_f32_16x16x32_bf16 v[80:83], v[178:181], v[18:21], v[80:83]
	v_mfma_f32_16x16x32_bf16 v[48:51], v[178:181], v[154:157], v[48:51]
	v_mfma_f32_16x16x32_bf16 v[140:143], v[182:185], v[10:13], v[140:143]
	v_mfma_f32_16x16x32_bf16 v[108:111], v[182:185], v[14:17], v[108:111]
	v_mfma_f32_16x16x32_bf16 v[76:79], v[182:185], v[18:21], v[76:79]
	v_mfma_f32_16x16x32_bf16 v[44:47], v[182:185], v[154:157], v[44:47]
	v_mfma_f32_16x16x32_bf16 v[136:139], v[192:195], v[10:13], v[136:139]
	v_mfma_f32_16x16x32_bf16 v[104:107], v[192:195], v[14:17], v[104:107]
	v_mfma_f32_16x16x32_bf16 v[72:75], v[192:195], v[18:21], v[72:75]
	v_mfma_f32_16x16x32_bf16 v[40:43], v[192:195], v[154:157], v[40:43]
	s_waitcnt vmcnt(6)
	s_waitcnt lgkmcnt(0)
	s_barrier
	s_add_u32 m0, s15, s16
	v_mfma_f32_16x16x32_bf16 v[132:135], v[196:199], v[10:13], v[132:135]
	global_load_lds_dwordx4 v0, s[98:99]
	v_mfma_f32_16x16x32_bf16 v[128:131], v[200:203], v[10:13], v[128:131]
	v_mfma_f32_16x16x32_bf16 v[124:127], v[204:207], v[10:13], v[124:127]
	global_load_lds_dwordx4 v1, s[98:99] offset:1024
	v_mfma_f32_16x16x32_bf16 v[120:123], v[232:235], v[10:13], v[120:123]
	v_mfma_f32_16x16x32_bf16 v[100:103], v[196:199], v[14:17], v[100:103]
	global_load_lds_dwordx4 v2, s[100:101] offset:2048
	v_mfma_f32_16x16x32_bf16 v[96:99], v[200:203], v[14:17], v[96:99]
	v_mfma_f32_16x16x32_bf16 v[92:95], v[204:207], v[14:17], v[92:95]
	global_load_lds_dwordx4 v3, s[100:101] offset:3072
	v_mfma_f32_16x16x32_bf16 v[88:91], v[232:235], v[14:17], v[88:91]
	v_mfma_f32_16x16x32_bf16 v[68:71], v[196:199], v[18:21], v[68:71]
	s_add_u32 m0, m0, 0x1000
	v_mfma_f32_16x16x32_bf16 v[64:67], v[200:203], v[18:21], v[64:67]
	global_load_lds_dwordx4 v4, s[100:101]
	v_mfma_f32_16x16x32_bf16 v[60:63], v[204:207], v[18:21], v[60:63]
	v_mfma_f32_16x16x32_bf16 v[56:59], v[232:235], v[18:21], v[56:59]
	v_mfma_f32_16x16x32_bf16 v[36:39], v[196:199], v[154:157], v[36:39]
	global_load_lds_dwordx4 v5, s[100:101] offset:1024
	v_mfma_f32_16x16x32_bf16 v[32:35], v[200:203], v[154:157], v[32:35]
	v_mfma_f32_16x16x32_bf16 v[28:31], v[204:207], v[154:157], v[28:31]
	v_mfma_f32_16x16x32_bf16 v[24:27], v[232:235], v[154:157], v[24:27]
	s_add_u32 s98, s98, 64
	s_addc_u32 s99, s99, 0
	s_add_u32 s100, s100, 0x10000
	s_addc_u32 s101, s101, 0
	s_add_u32 s15, s15, 0x6000
	s_cmp_eq_u32 s15, 0x12000
	s_cselect_b32 s15, 0, s15
	s_add_u32 s14, s14, 1
	s_branch .Lg843_end
; #define G_LOAD(PA, PB, STEP) do { _Pragma("unroll") for (int i_ = 0; i_ < 2; ++i_) ra[i_] = *(const u32x4*)((PA) + (size_t)(64 * i_) * K + (STEP) * 32); \
;         _Pragma("unroll") for (int i_ = 0; i_ < 4; ++i_) rb[i_] = *(const u32x4*)((PB) + (size_t)(64 * i_) * K + (STEP) * 32); } while (0)
; template <int EPI> ...
;     ...
;                 const bf16_t* pa = cur ? Ag : An; const bf16_t* pb = cur ? Bg : Bn;
;                 const int st = cur ? kt + 2 : kt + 2 - nk;
;                 G_LOAD(pa, pb, st);
;             }
;     ...
;                 } else {
;                     *(f32x4*)(xout + (size_t)m * Nn + n0) = v0;
;                     *(f32x4*)(xout + (size_t)m * Nn + n0 + 4) = v1;
.Lg843_sw:
	v_readlane_b32 vcc_lo, v253, 0
	v_readlane_b32 vcc_hi, v253, 1
	s_lshl_b32 s17, s12, 20
	s_nop 1
	s_add_u32 s98, vcc_lo, s17
	s_addc_u32 s99, vcc_hi, 0
	s_sub_u32 s98, s98, 0x1000
	s_subb_u32 s99, s99, 0
	v_readlane_b32 vcc_lo, v253, 2
	v_readlane_b32 vcc_hi, v253, 3
	s_lshl_b32 s17, s13, 14
	s_nop 1
	s_add_u32 s100, vcc_lo, s17
	s_addc_u32 s101, vcc_hi, 0
	s_sub_u32 s100, s100, 0x1000
	s_subb_u32 s101, s101, 0
	s_branch .Lg843_swret
.Lg843_end:
	s_setprio 0
	v_writelane_b32 v253, s15, 4
	v_readlane_b32 s12, v251, 34
	v_readlane_b32 s13, v251, 35
	v_readlane_b32 s14, v251, 36
	v_readlane_b32 s15, v251, 37
	v_readlane_b32 s16, v251, 38
	v_readlane_b32 s17, v251, 39
	v_readlane_b32 s18, v251, 40
	v_readlane_b32 s19, v251, 41
	v_readlane_b32 s20, v251, 42
	v_readlane_b32 s21, v251, 43
	v_readlane_b32 s22, v251, 44
	v_readlane_b32 s23, v251, 45
	v_or_b32_e32 v173, s11, v172
	v_readlane_b32 s24, v251, 46
	v_readlane_b32 s25, v251, 47
	v_readlane_b32 s26, v251, 48
	v_readlane_b32 s27, v251, 49
	s_mov_b64 s[12:13], s[16:17]
	v_lshl_add_u64 v[164:165], s[12:13], 0, v[164:165]
	v_lshlrev_b32_e32 v188, 2, v173
	v_lshl_add_u64 v[164:165], v[164:165], 0, v[188:189]
	global_store_dwordx4 v[164:165], v[148:151], off
	global_store_dwordx4 v[164:165], v[144:147], off offset:16
	global_store_dwordx4 v[164:165], v[140:143], off offset:128
	global_store_dwordx4 v[164:165], v[136:139], off offset:144
	global_store_dwordx4 v[164:165], v[132:135], off offset:256
	global_store_dwordx4 v[164:165], v[128:131], off offset:272
	global_store_dwordx4 v[164:165], v[124:127], off offset:384
	global_store_dwordx4 v[164:165], v[120:123], off offset:400
	s_and_b64 vcc, exec, s[6:7]
	s_mov_b64 s[14:15], s[18:19]
	v_lshl_add_u64 v[120:121], s[12:13], 0, v[162:163]
	v_lshl_add_u64 v[120:121], v[120:121], 0, v[188:189]
	global_store_dwordx4 v[120:121], v[116:119], off
	global_store_dwordx4 v[120:121], v[112:115], off offset:16
	global_store_dwordx4 v[120:121], v[108:111], off offset:128
	global_store_dwordx4 v[120:121], v[104:107], off offset:144
	global_store_dwordx4 v[120:121], v[100:103], off offset:256
	global_store_dwordx4 v[120:121], v[96:99], off offset:272
	global_store_dwordx4 v[120:121], v[92:95], off offset:384
	global_store_dwordx4 v[120:121], v[88:91], off offset:400
	s_mov_b64 s[16:17], s[20:21]
	s_mov_b64 s[18:19], s[22:23]
	v_lshl_add_u64 v[88:89], s[12:13], 0, v[160:161]
	v_lshl_add_u64 v[88:89], v[88:89], 0, v[188:189]
	global_store_dwordx4 v[88:89], v[84:87], off
	global_store_dwordx4 v[88:89], v[80:83], off offset:16
	global_store_dwordx4 v[88:89], v[76:79], off offset:128
	global_store_dwordx4 v[88:89], v[72:75], off offset:144
	global_store_dwordx4 v[88:89], v[68:71], off offset:256
	global_store_dwordx4 v[88:89], v[64:67], off offset:272
	global_store_dwordx4 v[88:89], v[60:63], off offset:384
	global_store_dwordx4 v[88:89], v[56:59], off offset:400
	s_mov_b64 s[20:21], s[24:25]
	s_mov_b64 s[22:23], s[26:27]
	v_lshl_add_u64 v[56:57], s[12:13], 0, v[158:159]
	v_lshl_add_u64 v[56:57], v[56:57], 0, v[188:189]
	global_store_dwordx4 v[56:57], v[52:55], off
	global_store_dwordx4 v[56:57], v[48:51], off offset:16
	global_store_dwordx4 v[56:57], v[44:47], off offset:128
	global_store_dwordx4 v[56:57], v[40:43], off offset:144
	global_store_dwordx4 v[56:57], v[36:39], off offset:256
	global_store_dwordx4 v[56:57], v[32:35], off offset:272
	global_store_dwordx4 v[56:57], v[28:31], off offset:384
	global_store_dwordx4 v[56:57], v[24:27], off offset:400
	s_cbranch_vccz .LBB0_842

; DI f32x4 mfma(bf16x8 a, bf16x8 b, f32x4 c) { return __builtin_amdgcn_mfma_f32_16x16x32_bf16(a, b, c, 0, 0, 0); }
; #define G_LOAD(PA, PB, STEP) do { _Pragma("unroll") for (int i_ = 0; i_ < 2; ++i_) ra[i_] = *(const u32x4*)((PA) + (size_t)(64 * i_) * K + (STEP) * 32); \
;         _Pragma("unroll") for (int i_ = 0; i_ < 4; ++i_) rb[i_] = *(const u32x4*)((PB) + (size_t)(64 * i_) * K + (STEP) * 32); } while (0)
; #define G_STORE(BUF) do { _Pragma("unroll") for (int i_ = 0; i_ < 2; ++i_) *(u32x4*)(sA + (BUF) * 128 * 40 + (lrow + 64 * i_) * 40 + lcc * 8) = ra[i_]; \
;         _Pragma("unroll") for (int i_ = 0; i_ < 4; ++i_) *(u32x4*)(sB + (BUF) * 256 * 40 + (lrow + 64 * i_) * 40 + lcc * 8) = rb[i_]; } while (0)
; template <int EPI> ...
;     ...
;     const int idx0 = blockIdx.x >> 3;
;     if (idx0 < perX) {
;         int mt0, nt0; tile_of(idx0, mt0, nt0);
;         const bf16_t* A0 = A + (size_t)(mt0 * 128 + lrow) * K + lcc * 8;
;         const bf16_t* B0 = Bt + (size_t)(nt0 * 256 + lrowp) * K + lcc * 8;
;         G_LOAD(A0, B0, 0);
;         G_STORE(0);
;         G_LOAD(A0, B0, 1);
;         __syncthreads();
;     }
;     ...
;         for (int kt = 0; kt < nk; ++kt) {
;             const int buf = kt & 1;
;             const bf16_t* a_ = sA + buf * 128 * 40 + (wr * 64 + fr) * 40 + fq * 8;
;             const bf16_t* b_ = sB + buf * 256 * 40 + (wc * 128 + fr) * 40 + fq * 8;
;             bf16x8 af[4];
; #pragma unroll
;             for (int i = 0; i < 4; ++i) af[i] = *(const bf16x8*)(a_ + i * 16 * 40);
; #pragma unroll
;             for (int jh = 0; jh < 2; ++jh) {
;                 bf16x8 bfr[4];
; #pragma unroll
;                 for (int j = 0; j < 4; ++j) bfr[j] = *(const bf16x8*)(b_ + (jh * 4 + j) * 16 * 40);
; #pragma unroll
;                 for (int i = 0; i < 4; ++i)
; #pragma unroll
;                     for (int j = 0; j < 4; ++j) acc[i][jh * 4 + j] = mfma(bfr[j], af[i], acc[i][jh * 4 + j]);
;             }
;             G_STORE(buf ^ 1);
;             {
;                 const bool cur = kt + 2 < nk;
;                 const bf16_t* pa = cur ? Ag : An; const bf16_t* pb = cur ? Bg : Bn;
;                 const int st = cur ? kt + 2 : kt + 2 - nk;
;                 G_LOAD(pa, pb, st);
;             }
.LBB0_853:
	v_readlane_b32 s15, v253, 4
	v_readlane_b32 s16, v253, 6
	v_readlane_b32 s17, v253, 5
	s_nop 3
	s_cmp_eq_u32 s17, 0
	s_cbranch_scc1 .Lg853_entry
	v_and_b32_e32 v8, 63, v210
	v_lshrrev_b32_e32 v9, 6, v210
	s_nop 0
	v_readfirstlane_b32 s17, v9
	v_lshrrev_b32_e32 v9, 4, v8
	v_sub_u32_e32 v10, 0, v9
	v_and_b32_e32 v10, 3, v10
	v_and_b32_e32 v11, 3, v8
	v_xor_b32_e32 v11, v11, v10
	v_lshrrev_b32_e32 v12, 2, v8
	v_lshlrev_b32_e32 v0, 13, v12
	v_lshl_add_u32 v0, v11, 4, v0
	s_lshl_b32 vcc_lo, s17, 18
	v_add_u32_e32 v0, vcc_lo, v0
	v_add_u32_e32 v0, 0x1000, v0
	v_add_u32_e32 v1, 0x1fc00, v0
	v_and_b32_e32 v13, 3, v12
	v_lshl_add_u32 v13, v9, 3, v13
	v_lshlrev_b32_e32 v2, 6, v13
	v_lshl_add_u32 v2, v11, 4, v2
	s_lshl_b32 vcc_lo, s17, 12
	v_add_u32_e32 v2, vcc_lo, v2
	v_add_u32_e32 v2, 0x800, v2
	v_add_u32_e32 v3, 0xfffffd00, v2
	v_add_u32_e32 v4, 0x1000, v2
	v_add_u32_e32 v5, 0xd00, v2
	v_and_b32_e32 v10, 15, v8
	v_lshrrev_b32_e32 v11, 2, v10
	v_sub_u32_e32 v11, 0, v11
	v_and_b32_e32 v11, 3, v11
	v_xor_b32_e32 v11, v9, v11
	v_lshlrev_b32_e32 v6, 6, v10
	v_lshl_add_u32 v6, v11, 4, v6
	s_lshr_b32 vcc_lo, s17, 1
	s_mul_i32 vcc_lo, vcc_lo, 0x3000
	s_and_b32 vcc_hi, s17, 1
	s_mul_i32 vcc_hi, vcc_hi, 0x3000
	s_add_u32 vcc_hi, vcc_hi, 0x800
	v_add_u32_e32 v7, vcc_hi, v6
	v_add_u32_e32 v6, vcc_lo, v6
	s_mul_i32 s16, s17, 0x1800
	v_writelane_b32 v253, s16, 6
	v_writelane_b32 v253, 0, 5
	v_readlane_b32 vcc_lo, v253, 0
	v_readlane_b32 vcc_hi, v253, 1
	s_lshl_b32 s17, s6, 20
	s_nop 1
	s_add_u32 s98, vcc_lo, s17
	s_addc_u32 s99, vcc_hi, 0
	s_sub_u32 s98, s98, 0x1000
	s_subb_u32 s99, s99, 0
	v_readlane_b32 vcc_lo, v253, 2
	v_readlane_b32 vcc_hi, v253, 3
	s_lshl_b32 s17, s7, 14
	s_nop 1
	s_add_u32 s100, vcc_lo, s17
	s_addc_u32 s101, vcc_hi, 0
	s_sub_u32 s100, s100, 0x1000
	s_subb_u32 s101, s101, 0
	s_add_u32 m0, s15, s16
	s_nop 0
	global_load_lds_dwordx4 v0, s[98:99]
	global_load_lds_dwordx4 v1, s[98:99] offset:1024
	global_load_lds_dwordx4 v2, s[100:101] offset:2048
	global_load_lds_dwordx4 v3, s[100:101] offset:3072
	s_add_u32 m0, m0, 0x1000
	s_nop 0
	global_load_lds_dwordx4 v4, s[100:101]
	global_load_lds_dwordx4 v5, s[100:101] offset:1024
	s_add_u32 s98, s98, 64
	s_addc_u32 s99, s99, 0
	s_add_u32 s100, s100, 0x10000
	s_addc_u32 s101, s101, 0
	s_add_u32 s17, s15, 0x6000
	s_cmp_eq_u32 s17, 0x12000
	s_cselect_b32 s17, 0, s17
	s_add_u32 m0, s17, s16
	s_nop 0
	global_load_lds_dwordx4 v0, s[98:99]
	global_load_lds_dwordx4 v1, s[98:99] offset:1024
	global_load_lds_dwordx4 v2, s[100:101] offset:2048
	global_load_lds_dwordx4 v3, s[100:101] offset:3072
	s_add_u32 m0, m0, 0x1000
	s_nop 0
	global_load_lds_dwordx4 v4, s[100:101]
	global_load_lds_dwordx4 v5, s[100:101] offset:1024
	s_add_u32 s98, s98, 64
	s_addc_u32 s99, s99, 0
	s_add_u32 s100, s100, 0x10000
	s_addc_u32 s101, s101, 0
	s_add_u32 s17, s17, 0x6000
	s_cmp_eq_u32 s17, 0x12000
	s_cselect_b32 s17, 0, s17
	s_add_u32 m0, s17, s16
	s_nop 0
	global_load_lds_dwordx4 v0, s[98:99]
	global_load_lds_dwordx4 v1, s[98:99] offset:1024
	global_load_lds_dwordx4 v2, s[100:101] offset:2048
	global_load_lds_dwordx4 v3, s[100:101] offset:3072
	s_add_u32 m0, m0, 0x1000
	s_nop 0
	global_load_lds_dwordx4 v4, s[100:101]
	global_load_lds_dwordx4 v5, s[100:101] offset:1024
	s_add_u32 s98, s98, 64
	s_addc_u32 s99, s99, 0
	s_add_u32 s100, s100, 0x10000
	s_addc_u32 s101, s101, 0

; DI f32x4 mfma(bf16x8 a, bf16x8 b, f32x4 c) { return __builtin_amdgcn_mfma_f32_16x16x32_bf16(a, b, c, 0, 0, 0); }
; #define G_LOAD(PA, PB, STEP) do { _Pragma("unroll") for (int i_ = 0; i_ < 2; ++i_) ra[i_] = *(const u32x4*)((PA) + (size_t)(64 * i_) * K + (STEP) * 32); \
;         _Pragma("unroll") for (int i_ = 0; i_ < 4; ++i_) rb[i_] = *(const u32x4*)((PB) + (size_t)(64 * i_) * K + (STEP) * 32); } while (0)
; #define G_STORE(BUF) do { _Pragma("unroll") for (int i_ = 0; i_ < 2; ++i_) *(u32x4*)(sA + (BUF) * 128 * 40 + (lrow + 64 * i_) * 40 + lcc * 8) = ra[i_]; \
;         _Pragma("unroll") for (int i_ = 0; i_ < 4; ++i_) *(u32x4*)(sB + (BUF) * 256 * 40 + (lrow + 64 * i_) * 40 + lcc * 8) = rb[i_]; } while (0)
; template <int EPI> ...
;     ...
;         for (int kt = 0; kt < nk; ++kt) {
;             const int buf = kt & 1;
;             const bf16_t* a_ = sA + buf * 128 * 40 + (wr * 64 + fr) * 40 + fq * 8;
;             const bf16_t* b_ = sB + buf * 256 * 40 + (wc * 128 + fr) * 40 + fq * 8;
;             bf16x8 af[4];
; #pragma unroll
;             for (int i = 0; i < 4; ++i) af[i] = *(const bf16x8*)(a_ + i * 16 * 40);
; #pragma unroll
;             for (int jh = 0; jh < 2; ++jh) {
;                 bf16x8 bfr[4];
; #pragma unroll
;                 for (int j = 0; j < 4; ++j) bfr[j] = *(const bf16x8*)(b_ + (jh * 4 + j) * 16 * 40);
; #pragma unroll
;                 for (int i = 0; i < 4; ++i)
; #pragma unroll
;                     for (int j = 0; j < 4; ++j) acc[i][jh * 4 + j] = mfma(bfr[j], af[i], acc[i][jh * 4 + j]);
;             }
;             G_STORE(buf ^ 1);
;             {
;                 const bool cur = kt + 2 < nk;
;                 const bf16_t* pa = cur ? Ag : An; const bf16_t* pb = cur ? Bg : Bn;
;                 const int st = cur ? kt + 2 : kt + 2 - nk;
;                 G_LOAD(pa, pb, st);
;             }
;             __syncthreads();
;         }
.Lg853_swret:
	s_add_u32 m0, s15, s16
	v_mfma_f32_16x16x32_bf16 v[132:135], v[204:207], v[10:13], v[132:135]
	global_load_lds_dwordx4 v0, s[98:99]
	v_mfma_f32_16x16x32_bf16 v[128:131], v[232:235], v[10:13], v[128:131]
	v_mfma_f32_16x16x32_bf16 v[124:127], v[236:239], v[10:13], v[124:127]
	global_load_lds_dwordx4 v1, s[98:99] offset:1024
	v_mfma_f32_16x16x32_bf16 v[120:123], v[240:243], v[10:13], v[120:123]
	ds_read_b128 v[10:13], v8
	v_mfma_f32_16x16x32_bf16 v[100:103], v[204:207], v[14:17], v[100:103]
	global_load_lds_dwordx4 v2, s[100:101] offset:2048
	v_mfma_f32_16x16x32_bf16 v[96:99], v[232:235], v[14:17], v[96:99]
	v_mfma_f32_16x16x32_bf16 v[92:95], v[236:239], v[14:17], v[92:95]
	global_load_lds_dwordx4 v3, s[100:101] offset:3072
	v_mfma_f32_16x16x32_bf16 v[88:91], v[240:243], v[14:17], v[88:91]
	ds_read_b128 v[14:17], v8 offset:1024
	v_mfma_f32_16x16x32_bf16 v[68:71], v[204:207], v[18:21], v[68:71]
	s_add_u32 m0, m0, 0x1000
	v_mfma_f32_16x16x32_bf16 v[64:67], v[232:235], v[18:21], v[64:67]
	global_load_lds_dwordx4 v4, s[100:101]
	v_mfma_f32_16x16x32_bf16 v[60:63], v[236:239], v[18:21], v[60:63]
	v_mfma_f32_16x16x32_bf16 v[56:59], v[240:243], v[18:21], v[56:59]
	ds_read_b128 v[18:21], v8 offset:6144
	v_mfma_f32_16x16x32_bf16 v[36:39], v[204:207], v[154:157], v[36:39]
	global_load_lds_dwordx4 v5, s[100:101] offset:1024
	v_mfma_f32_16x16x32_bf16 v[32:35], v[232:235], v[154:157], v[32:35]
	v_mfma_f32_16x16x32_bf16 v[28:31], v[236:239], v[154:157], v[28:31]
	v_mfma_f32_16x16x32_bf16 v[24:27], v[240:243], v[154:157], v[24:27]
	ds_read_b128 v[154:157], v8 offset:7168
	ds_read_b128 v[204:207], v9 offset:6144
	ds_read_b128 v[232:235], v9 offset:7168
	ds_read_b128 v[236:239], v9 offset:8192
	ds_read_b128 v[240:243], v9 offset:9216
	s_add_u32 s98, s98, 64
	s_addc_u32 s99, s99, 0
	s_add_u32 s100, s100, 0x10000
	s_addc_u32 s101, s101, 0
	s_add_u32 s15, s15, 0x6000
	s_cmp_eq_u32 s15, 0x12000
	s_cselect_b32 s15, 0, s15
	s_add_u32 s14, s14, 1
	s_cmp_lt_u32 s14, 127
	s_cbranch_scc1 .Lg853_top
	s_waitcnt lgkmcnt(4)
	v_mfma_f32_16x16x32_bf16 v[148:151], v[174:177], v[10:13], v[148:151]
	v_mfma_f32_16x16x32_bf16 v[116:119], v[174:177], v[14:17], v[116:119]
	v_mfma_f32_16x16x32_bf16 v[84:87], v[174:177], v[18:21], v[84:87]
	v_mfma_f32_16x16x32_bf16 v[52:55], v[174:177], v[154:157], v[52:55]
	v_mfma_f32_16x16x32_bf16 v[144:147], v[192:195], v[10:13], v[144:147]
	v_mfma_f32_16x16x32_bf16 v[112:115], v[192:195], v[14:17], v[112:115]
	v_mfma_f32_16x16x32_bf16 v[80:83], v[192:195], v[18:21], v[80:83]
	v_mfma_f32_16x16x32_bf16 v[48:51], v[192:195], v[154:157], v[48:51]
	v_mfma_f32_16x16x32_bf16 v[140:143], v[196:199], v[10:13], v[140:143]
	v_mfma_f32_16x16x32_bf16 v[108:111], v[196:199], v[14:17], v[108:111]
	v_mfma_f32_16x16x32_bf16 v[76:79], v[196:199], v[18:21], v[76:79]
	v_mfma_f32_16x16x32_bf16 v[44:47], v[196:199], v[154:157], v[44:47]
	v_mfma_f32_16x16x32_bf16 v[136:139], v[200:203], v[10:13], v[136:139]
	v_mfma_f32_16x16x32_bf16 v[104:107], v[200:203], v[14:17], v[104:107]
	v_mfma_f32_16x16x32_bf16 v[72:75], v[200:203], v[18:21], v[72:75]
	v_mfma_f32_16x16x32_bf16 v[40:43], v[200:203], v[154:157], v[40:43]
	s_waitcnt vmcnt(6)
	s_waitcnt lgkmcnt(0)
	s_barrier
	s_add_u32 m0, s15, s16
	v_mfma_f32_16x16x32_bf16 v[132:135], v[204:207], v[10:13], v[132:135]
	global_load_lds_dwordx4 v0, s[98:99]
	v_mfma_f32_16x16x32_bf16 v[128:131], v[232:235], v[10:13], v[128:131]
	v_mfma_f32_16x16x32_bf16 v[124:127], v[236:239], v[10:13], v[124:127]
	global_load_lds_dwordx4 v1, s[98:99] offset:1024
	v_mfma_f32_16x16x32_bf16 v[120:123], v[240:243], v[10:13], v[120:123]
	v_mfma_f32_16x16x32_bf16 v[100:103], v[204:207], v[14:17], v[100:103]
	global_load_lds_dwordx4 v2, s[100:101] offset:2048
	v_mfma_f32_16x16x32_bf16 v[96:99], v[232:235], v[14:17], v[96:99]
	v_mfma_f32_16x16x32_bf16 v[92:95], v[236:239], v[14:17], v[92:95]
	global_load_lds_dwordx4 v3, s[100:101] offset:3072
	v_mfma_f32_16x16x32_bf16 v[88:91], v[240:243], v[14:17], v[88:91]
	v_mfma_f32_16x16x32_bf16 v[68:71], v[204:207], v[18:21], v[68:71]
	s_add_u32 m0, m0, 0x1000
	v_mfma_f32_16x16x32_bf16 v[64:67], v[232:235], v[18:21], v[64:67]
	global_load_lds_dwordx4 v4, s[100:101]
	v_mfma_f32_16x16x32_bf16 v[60:63], v[236:239], v[18:21], v[60:63]
	v_mfma_f32_16x16x32_bf16 v[56:59], v[240:243], v[18:21], v[56:59]
	v_mfma_f32_16x16x32_bf16 v[36:39], v[204:207], v[154:157], v[36:39]
	global_load_lds_dwordx4 v5, s[100:101] offset:1024
	v_mfma_f32_16x16x32_bf16 v[32:35], v[232:235], v[154:157], v[32:35]
	v_mfma_f32_16x16x32_bf16 v[28:31], v[236:239], v[154:157], v[28:31]
	v_mfma_f32_16x16x32_bf16 v[24:27], v[240:243], v[154:157], v[24:27]
	s_add_u32 s98, s98, 64
	s_addc_u32 s99, s99, 0
	s_add_u32 s100, s100, 0x10000
	s_addc_u32 s101, s101, 0
	s_add_u32 s15, s15, 0x6000
	s_cmp_eq_u32 s15, 0x12000
	s_cselect_b32 s15, 0, s15
	s_add_u32 s14, s14, 1
	s_branch .Lg853_end
; DI unsigned pk2(float lo, float hi) { f32x2 v = {lo, hi}; bf16x2_t r = __builtin_convertvector(v, bf16x2_t); return __builtin_bit_cast(unsigned, r); }
; #define G_LOAD(PA, PB, STEP) do { _Pragma("unroll") for (int i_ = 0; i_ < 2; ++i_) ra[i_] = *(const u32x4*)((PA) + (size_t)(64 * i_) * K + (STEP) * 32); \
;         _Pragma("unroll") for (int i_ = 0; i_ < 4; ++i_) rb[i_] = *(const u32x4*)((PB) + (size_t)(64 * i_) * K + (STEP) * 32); } while (0)
; template <int EPI> ...
;     ...
;                 const bf16_t* pa = cur ? Ag : An; const bf16_t* pb = cur ? Bg : Bn;
;                 const int st = cur ? kt + 2 : kt + 2 - nk;
;                 G_LOAD(pa, pb, st);
;             }
;     ...
;                 } else {
;                     *(f32x4*)(xout + (size_t)m * Nn + n0) = v0;
;                     *(f32x4*)(xout + (size_t)m * Nn + n0 + 4) = v1;
;                     if (hb) {
;                         const f32x4 g0 = *(const f32x4*)(gn + n0), g1 = *(const f32x4*)(gn + n0 + 4);
;                         u32x4 o4; o4[0] = pk2(v0[0] * g0[0], v0[1] * g0[1]); o4[1] = pk2(v0[2] * g0[2], v0[3] * g0[3]);
;                         o4[2] = pk2(v1[0] * g1[0], v1[1] * g1[1]); o4[3] = pk2(v1[2] * g1[2], v1[3] * g1[3]);
;                         *(u32x4*)(hb + (size_t)m * Nn + n0) = o4;
;                         sq += v0[0] * v0[0] + v0[1] * v0[1] + v0[2] * v0[2] + v0[3] * v0[3] + v1[0] * v1[0] + v1[1] * v1[1] + v1[2] * v1[2] + v1[3] * v1[3];
;                     }
.Lg853_sw:
	v_readlane_b32 vcc_lo, v253, 0
	v_readlane_b32 vcc_hi, v253, 1
	s_lshl_b32 s17, s11, 20
	s_nop 1
	s_add_u32 s98, vcc_lo, s17
	s_addc_u32 s99, vcc_hi, 0
	s_sub_u32 s98, s98, 0x1000
	s_subb_u32 s99, s99, 0
	v_readlane_b32 vcc_lo, v253, 2
	v_readlane_b32 vcc_hi, v253, 3
	s_lshl_b32 s17, s13, 14
	s_nop 1
	s_add_u32 s100, vcc_lo, s17
	s_addc_u32 s101, vcc_hi, 0
	s_sub_u32 s100, s100, 0x1000
	s_subb_u32 s101, s101, 0
	s_branch .Lg853_swret
.Lg853_end:
	s_setprio 0
	v_writelane_b32 v253, s15, 4
	v_readlane_b32 s52, v251, 34
	v_readlane_b32 s53, v251, 35
	v_readlane_b32 s54, v251, 36
	v_readlane_b32 s55, v251, 37
	v_readlane_b32 s56, v251, 38
	v_readlane_b32 s57, v251, 39
	v_readlane_b32 s58, v251, 40
	v_readlane_b32 s59, v251, 41
	v_readlane_b32 s60, v251, 42
	v_readlane_b32 s61, v251, 43
	v_readlane_b32 s62, v251, 44
	v_readlane_b32 s63, v251, 45
	v_readlane_b32 s64, v251, 46
	v_readlane_b32 s65, v251, 47
	v_readlane_b32 s66, v251, 48
	v_readlane_b32 s67, v251, 49
	v_or_b32_e32 v185, s10, v184
	v_lshl_add_u64 v[164:165], s[56:57], 0, v[164:165]
	v_readlane_b32 s52, v250, 51
	v_readlane_b32 s6, v250, 42
	v_lshlrev_b64 v[174:175], 11, v[170:171]
	v_readlane_b32 s54, v250, 53
	v_readlane_b32 s55, v250, 54
	v_lshlrev_b32_e32 v188, 2, v185
	v_readlane_b32 s7, v250, 43
	v_lshl_add_u64 v[174:175], s[54:55], 0, v[174:175]
	v_lshl_add_u64 v[176:177], v[164:165], 0, v[188:189]
	s_and_b64 vcc, exec, s[6:7]
	v_lshlrev_b32_e32 v164, 1, v185
	v_readlane_b32 s53, v250, 52
	v_readlane_b32 s56, v250, 55
	v_readlane_b32 s57, v250, 56
	v_readlane_b32 s58, v250, 57
	v_readlane_b32 s59, v250, 58
	v_readlane_b32 s60, v250, 59
	v_readlane_b32 s61, v250, 60
	v_readlane_b32 s62, v250, 61
	v_readlane_b32 s63, v250, 62
	v_readlane_b32 s64, v250, 63
	v_readlane_b32 s65, v249, 0
	v_readlane_b32 s66, v249, 1
	v_readlane_b32 s67, v249, 2
	global_store_dwordx4 v[176:177], v[148:151], off
	global_store_dwordx4 v[176:177], v[144:147], off offset:16
	s_cbranch_vccz .LBB0_856
	v_readlane_b32 s6, v250, 40
	v_readlane_b32 s7, v250, 41
	s_nop 4
	global_load_dwordx4 v[192:195], v188, s[6:7] offset:16
	global_load_dwordx4 v[196:199], v188, s[6:7]
	v_mov_b32_e32 v165, v189
	s_waitcnt vmcnt(1)
	v_pk_mul_f32 v[192:193], v[144:145], v[192:193]
	s_waitcnt vmcnt(0)
	v_pk_mul_f32 v[196:197], v[148:149], v[196:197]
	v_pk_mul_f32 v[148:149], v[148:149], v[148:149]
	v_pk_mul_f32 v[186:187], v[150:151], v[198:199]
	v_pk_mul_f32 v[150:151], v[150:151], v[150:151]
	v_add_f32_e32 v148, v148, v149
	v_add_f32_e32 v148, v150, v148
	v_pk_mul_f32 v[144:145], v[144:145], v[144:145]
	v_add_f32_e32 v148, v151, v148
	v_add_f32_e32 v144, v144, v148
	v_cvt_pk_bf16_f32 v196, v196, v197
	v_cvt_pk_bf16_f32 v197, v186, v187
	v_pk_mul_f32 v[186:187], v[146:147], v[194:195]
	v_pk_mul_f32 v[146:147], v[146:147], v[146:147]
	v_add_f32_e32 v144, v145, v144
	v_add_f32_e32 v144, v146, v144
	v_cvt_pk_bf16_f32 v198, v192, v193
	v_cvt_pk_bf16_f32 v199, v186, v187
	v_lshl_add_u64 v[186:187], v[174:175], 0, v[164:165]
	v_add_f32_e32 v145, v147, v144
	global_store_dwordx4 v[186:187], v[196:199], off
	s_branch .LBB0_857

; __global__ void __launch_bounds__(256, 2) mega_kernel(Params p) {
	.amdhsa_kernel _Z11mega_kernel6Params
		.amdhsa_group_segment_fixed_size 0
		.amdhsa_private_segment_fixed_size 0
		.amdhsa_kernarg_size 592
		.amdhsa_user_sgpr_count 2
		.amdhsa_user_sgpr_dispatch_ptr 0
		.amdhsa_user_sgpr_queue_ptr 0
		.amdhsa_user_sgpr_kernarg_segment_ptr 1
		.amdhsa_user_sgpr_dispatch_id 0
		.amdhsa_user_sgpr_kernarg_preload_length 0
		.amdhsa_user_sgpr_kernarg_preload_offset 0
		.amdhsa_user_sgpr_private_segment_size 0
		.amdhsa_uses_dynamic_stack 0
		.amdhsa_enable_private_segment 0
		.amdhsa_system_sgpr_workgroup_id_x 1
		.amdhsa_system_sgpr_workgroup_id_y 0
		.amdhsa_system_sgpr_workgroup_id_z 0
		.amdhsa_system_sgpr_workgroup_info 0
		.amdhsa_system_vgpr_workitem_id 2
		.amdhsa_next_free_vgpr 256
		.amdhsa_next_free_sgpr 102
		.amdhsa_accum_offset 256
		.amdhsa_reserve_vcc 1
		.amdhsa_float_round_mode_32 0
		.amdhsa_float_round_mode_16_64 0
		.amdhsa_float_denorm_mode_32 3
		.amdhsa_float_denorm_mode_16_64 3
		.amdhsa_dx10_clamp 1
		.amdhsa_ieee_mode 1
		.amdhsa_fp16_overflow 0
		.amdhsa_tg_split 0
		.amdhsa_exception_fp_ieee_invalid_op 0
		.amdhsa_exception_fp_denorm_src 0
		.amdhsa_exception_fp_ieee_div_zero 0
		.amdhsa_exception_fp_ieee_overflow 0
		.amdhsa_exception_fp_ieee_underflow 0
		.amdhsa_exception_fp_ieee_inexact 0
		.amdhsa_exception_int_div_zero 0
	.end_amdhsa_kernel

; __global__ void __launch_bounds__(256, 2) mega_kernel(Params p) {
amdhsa.kernels:
  - .agpr_count:     0
    .args:
      - .offset:         0
        .size:           336
        .value_kind:     by_value
      - .offset:         336
        .size:           4
        .value_kind:     hidden_block_count_x
      - .offset:         340
        .size:           4
        .value_kind:     hidden_block_count_y
      - .offset:         344
        .size:           4
        .value_kind:     hidden_block_count_z
      - .offset:         348
        .size:           2
        .value_kind:     hidden_group_size_x
      - .offset:         350
        .size:           2
        .value_kind:     hidden_group_size_y
      - .offset:         352
        .size:           2
        .value_kind:     hidden_group_size_z
      - .offset:         354
        .size:           2
        .value_kind:     hidden_remainder_x
      - .offset:         356
        .size:           2
        .value_kind:     hidden_remainder_y
      - .offset:         358
        .size:           2
        .value_kind:     hidden_remainder_z
      - .offset:         376
        .size:           8
        .value_kind:     hidden_global_offset_x
      - .offset:         384
        .size:           8
        .value_kind:     hidden_global_offset_y
      - .offset:         392
        .size:           8
        .value_kind:     hidden_global_offset_z
      - .offset:         400
        .size:           2
        .value_kind:     hidden_grid_dims
      - .offset:         424
        .size:           8
        .value_kind:     hidden_multigrid_sync_arg
      - .offset:         456
        .size:           4
        .value_kind:     hidden_dynamic_lds_size
    .group_segment_fixed_size: 0
    .kernarg_segment_align: 8
    .kernarg_segment_size: 592
    .language:       OpenCL C
    .language_version:
      - 2
      - 0
    .max_flat_workgroup_size: 256
    .name:           _Z11mega_kernel6Params
    .private_segment_fixed_size: 0
    .sgpr_count:     108
    .sgpr_spill_count: 284
    .symbol:         _Z11mega_kernel6Params.kd
    .uniform_work_group_size: 1
    .uses_dynamic_stack: false
    .vgpr_count:     256
    .vgpr_spill_count: 0
    .wavefront_size: 64
